# removed the redundant mid-block s_setprio 0/1 pair between the two 16-MFMA halves in all five GEMM K-loops (timing-only change)
# baseline (speedup 1.0000x reference)
; #define PG8_STAGE(bufoff, gbase, voff) do { _Pragma("unroll") for (int _i = 0; _i < 2; ++_i) \
;         __builtin_amdgcn_global_load_lds((const __attribute__((address_space(1))) unsigned*)((const char*)(gbase) + (voff)[_i]), (LAS unsigned*)(lds + (bufoff) + ldsw + _i * 8192), 16, 0, 0); } while (0)
; #define PG8_LDA(dst, b, h) do { _Pragma("unroll") for (int m = 0; m < 4; ++m) _Pragma("unroll") for (int k = 0; k < 2; ++k) dst[m][k] = *(const LAS bf16x8*)(lds + PG8_SA(b, h) + aoff + m * 2048 + k * 1024); } while (0)
; #define PG8_LDB(dst, b, h) do { _Pragma("unroll") for (int n = 0; n < 2; ++n) _Pragma("unroll") for (int k = 0; k < 2; ++k) dst[n][k] = *(const LAS bf16x8*)(lds + PG8_SB(b, h) + boff + n * 2048 + k * 1024); } while (0)
; #define PG8_MMA(ai, bj, At, Bt) do { __builtin_amdgcn_s_setprio(1); _Pragma("unroll") for (int m = 0; m < 4; ++m) _Pragma("unroll") for (int n = 0; n < 2; ++n) _Pragma("unroll") for (int k = 0; k < 2; ++k) \
;         acc[ai][bj][m][n] = __builtin_amdgcn_mfma_f32_16x16x32_bf16(Bt[n][k], At[m][k], acc[ai][bj][m][n], 0, 0, 0); __builtin_amdgcn_s_setprio(0); } while (0)
; #define PG8_WAIT_V(n) asm volatile("s_waitcnt vmcnt(" #n ")" ::: "memory")
; #define PG8_WAIT_L(n) asm volatile("s_waitcnt lgkmcnt(" #n ")" ::: "memory")
; #define PG8_BAR __builtin_amdgcn_s_barrier()
; #define PG8_SCHED __builtin_amdgcn_sched_barrier(0)
; template <class Epi, class SchedT, bool ALIGN_EPI, bool SP2>
; __device__ __forceinline__ void gemm_phase(LAS unsigned char* lds, const int ldk, const int nt, const SchedT& S, const Epi& E) {
;     ...
;             if constexpr (SP2) {
;             PG8_LDB(B0, 0, 0); PG8_LDB(B1, 0, 1); PG8_SCHED; PG8_LDA(At, 0, 0); PG8_STAGE(PG8_SA(1, 1), a1 + hstep, voffA);
;             PG8_WAIT_V(8); PG8_WAIT_L(0); PG8_BAR; PG8_MMA(0, 0, At, B0); PG8_MMA(0, 1, At, B1); PG8_BAR; PG8_SCHED;
;             PG8_LDA(At, 0, 1); PG8_STAGE(PG8_SB(0, 0), b2, voffB); PG8_STAGE(PG8_SB(0, 1), b2 + hstepB, voffB); PG8_STAGE(PG8_SA(0, 0), a2, voffA);
;             PG8_WAIT_V(8); PG8_WAIT_L(0); PG8_BAR; PG8_MMA(1, 0, At, B0); PG8_MMA(1, 1, At, B1); PG8_BAR; PG8_SCHED;
.LBB0_123:
	s_add_u32 s12, s0, 0xfff80080
	s_addc_u32 s13, s1, -1
	s_add_i32 s34, 0, 0x10000
	s_cmp_eq_u32 s21, 28
	s_cselect_b32 s17, s61, s13
	s_cselect_b32 s16, s60, s12
	v_add_u32_e32 v0, s34, v212
	s_cselect_b32 s13, s31, s19
	s_cselect_b32 s12, s30, s18
	s_add_i32 s38, 0, 0x14000
	s_waitcnt lgkmcnt(0)
	ds_read_b128 v[132:135], v0
	ds_read_b128 v[136:139], v0 offset:1024
	ds_read_b128 v[140:143], v0 offset:2048
	ds_read_b128 v[144:147], v0 offset:3072
	v_add_u32_e32 v0, s38, v212
	ds_read_b128 v[148:151], v0
	ds_read_b128 v[152:155], v0 offset:1024
	ds_read_b128 v[184:187], v0 offset:2048
	ds_read_b128 v[188:191], v0 offset:3072
	v_lshl_add_u64 v[2:3], s[0:1], 0, v[180:181]
	s_add_i32 m0, s88, 0xc000
	ds_read_b128 v[192:195], v216
	ds_read_b128 v[196:199], v216 offset:1024
	ds_read_b128 v[200:203], v216 offset:2048
	ds_read_b128 v[204:207], v216 offset:3072
	ds_read_b128 v[218:221], v216 offset:4096
	ds_read_b128 v[222:225], v216 offset:5120
	ds_read_b128 v[226:229], v216 offset:6144
	ds_read_b128 v[230:233], v216 offset:7168
	global_load_lds_dwordx4 v[2:3], off
	v_lshl_add_u64 v[2:3], s[0:1], 0, v[182:183]
	s_add_i32 m0, s88, 0xe000
	s_nop 0
	global_load_lds_dwordx4 v[2:3], off
	s_waitcnt vmcnt(8)
	s_waitcnt lgkmcnt(0)
	s_barrier
	s_setprio 1
	s_waitcnt lgkmcnt(0)
	v_mfma_f32_16x16x32_bf16 v[128:131], v[132:135], v[192:195], v[128:131]
	v_mfma_f32_16x16x32_bf16 v[124:127], v[140:143], v[192:195], v[124:127]
	v_mfma_f32_16x16x32_bf16 v[112:115], v[132:135], v[200:203], v[112:115]
	v_mfma_f32_16x16x32_bf16 v[108:111], v[140:143], v[200:203], v[108:111]
	v_mfma_f32_16x16x32_bf16 v[96:99], v[132:135], v[218:221], v[96:99]
	v_mfma_f32_16x16x32_bf16 v[92:95], v[140:143], v[218:221], v[92:95]
	v_mfma_f32_16x16x32_bf16 v[80:83], v[132:135], v[226:229], v[80:83]
	v_mfma_f32_16x16x32_bf16 v[76:79], v[140:143], v[226:229], v[76:79]
	v_mfma_f32_16x16x32_bf16 v[128:131], v[136:139], v[196:199], v[128:131]
	v_mfma_f32_16x16x32_bf16 v[124:127], v[144:147], v[196:199], v[124:127]
	v_mfma_f32_16x16x32_bf16 v[112:115], v[136:139], v[204:207], v[112:115]
	v_mfma_f32_16x16x32_bf16 v[108:111], v[144:147], v[204:207], v[108:111]
	v_mfma_f32_16x16x32_bf16 v[96:99], v[136:139], v[222:225], v[96:99]
	v_mfma_f32_16x16x32_bf16 v[92:95], v[144:147], v[222:225], v[92:95]
	v_mfma_f32_16x16x32_bf16 v[80:83], v[136:139], v[230:233], v[80:83]
	v_mfma_f32_16x16x32_bf16 v[76:79], v[144:147], v[230:233], v[76:79]
	v_mfma_f32_16x16x32_bf16 v[120:123], v[148:151], v[192:195], v[120:123]
	v_mfma_f32_16x16x32_bf16 v[116:119], v[184:187], v[192:195], v[116:119]
	v_mfma_f32_16x16x32_bf16 v[104:107], v[148:151], v[200:203], v[104:107]
	v_mfma_f32_16x16x32_bf16 v[100:103], v[184:187], v[200:203], v[100:103]
	v_mfma_f32_16x16x32_bf16 v[88:91], v[148:151], v[218:221], v[88:91]
	v_mfma_f32_16x16x32_bf16 v[84:87], v[184:187], v[218:221], v[84:87]
	v_mfma_f32_16x16x32_bf16 v[72:75], v[148:151], v[226:229], v[72:75]
	v_mfma_f32_16x16x32_bf16 v[68:71], v[184:187], v[226:229], v[68:71]
	v_mfma_f32_16x16x32_bf16 v[120:123], v[152:155], v[196:199], v[120:123]
	v_mfma_f32_16x16x32_bf16 v[116:119], v[188:191], v[196:199], v[116:119]
	v_mfma_f32_16x16x32_bf16 v[104:107], v[152:155], v[204:207], v[104:107]
	v_mfma_f32_16x16x32_bf16 v[100:103], v[188:191], v[204:207], v[100:103]
	v_mfma_f32_16x16x32_bf16 v[88:91], v[152:155], v[222:225], v[88:91]
	v_mfma_f32_16x16x32_bf16 v[84:87], v[188:191], v[222:225], v[84:87]
	v_mfma_f32_16x16x32_bf16 v[72:75], v[152:155], v[230:233], v[72:75]
	v_mfma_f32_16x16x32_bf16 v[68:71], v[188:191], v[230:233], v[68:71]
	s_setprio 0
	s_barrier
	s_add_i32 s34, s34, s87
	v_lshl_add_u64 v[208:209], s[12:13], 0, v[158:159]
	s_mov_b32 m0, s34
	ds_read_b128 v[192:195], v216 offset:16384
	ds_read_b128 v[196:199], v216 offset:17408
	ds_read_b128 v[200:203], v216 offset:18432
	ds_read_b128 v[204:207], v216 offset:19456
	ds_read_b128 v[218:221], v216 offset:20480
	ds_read_b128 v[222:225], v216 offset:21504
	ds_read_b128 v[226:229], v216 offset:22528
	ds_read_b128 v[230:233], v216 offset:23552
	global_load_lds_dwordx4 v[208:209], off
	s_add_i32 m0, s34, 0x2000
	s_add_u32 s34, s12, 0x20000
	v_lshl_add_u64 v[234:235], s[12:13], 0, v[174:175]
	s_addc_u32 s35, s13, 0
	s_add_i32 s38, s38, s87
	global_load_lds_dwordx4 v[234:235], off
	v_lshl_add_u64 v[2:3], s[34:35], 0, v[158:159]
	s_mov_b32 m0, s38
	v_lshl_add_u64 v[236:237], s[16:17], 0, v[156:157]
	global_load_lds_dwordx4 v[2:3], off
	v_lshl_add_u64 v[2:3], s[34:35], 0, v[174:175]
	s_add_i32 m0, s38, 0x2000
	v_lshl_add_u64 v[238:239], s[16:17], 0, v[160:161]
	global_load_lds_dwordx4 v[2:3], off
	s_mov_b32 m0, s88
	s_nop 0
	global_load_lds_dwordx4 v[236:237], off
	s_mov_b32 m0, s89
	s_nop 0
	global_load_lds_dwordx4 v[238:239], off
	s_waitcnt vmcnt(8)
	s_waitcnt lgkmcnt(0)
	s_barrier
; #define PG8_STAGE(bufoff, gbase, voff) do { _Pragma("unroll") for (int _i = 0; _i < 2; ++_i) \
;         __builtin_amdgcn_global_load_lds((const __attribute__((address_space(1))) unsigned*)((const char*)(gbase) + (voff)[_i]), (LAS unsigned*)(lds + (bufoff) + ldsw + _i * 8192), 16, 0, 0); } while (0)
; #define PG8_LDA(dst, b, h) do { _Pragma("unroll") for (int m = 0; m < 4; ++m) _Pragma("unroll") for (int k = 0; k < 2; ++k) dst[m][k] = *(const LAS bf16x8*)(lds + PG8_SA(b, h) + aoff + m * 2048 + k * 1024); } while (0)
; #define PG8_LDB(dst, b, h) do { _Pragma("unroll") for (int n = 0; n < 2; ++n) _Pragma("unroll") for (int k = 0; k < 2; ++k) dst[n][k] = *(const LAS bf16x8*)(lds + PG8_SB(b, h) + boff + n * 2048 + k * 1024); } while (0)
; #define PG8_MMA(ai, bj, At, Bt) do { __builtin_amdgcn_s_setprio(1); _Pragma("unroll") for (int m = 0; m < 4; ++m) _Pragma("unroll") for (int n = 0; n < 2; ++n) _Pragma("unroll") for (int k = 0; k < 2; ++k) \
;         acc[ai][bj][m][n] = __builtin_amdgcn_mfma_f32_16x16x32_bf16(Bt[n][k], At[m][k], acc[ai][bj][m][n], 0, 0, 0); __builtin_amdgcn_s_setprio(0); } while (0)
; #define PG8_WAIT_V(n) asm volatile("s_waitcnt vmcnt(" #n ")" ::: "memory")
; #define PG8_WAIT_L(n) asm volatile("s_waitcnt lgkmcnt(" #n ")" ::: "memory")
; #define PG8_BAR __builtin_amdgcn_s_barrier()
; #define PG8_SCHED __builtin_amdgcn_sched_barrier(0)
; template <class Epi, class SchedT, bool ALIGN_EPI, bool SP2>
; __device__ __forceinline__ void gemm_phase(LAS unsigned char* lds, const int ldk, const int nt, const SchedT& S, const Epi& E) {
;     ...
;             PG8_WAIT_V(8); PG8_WAIT_L(0); PG8_BAR; PG8_MMA(1, 0, At, B0); PG8_MMA(1, 1, At, B1); PG8_BAR; PG8_SCHED;
;             PG8_LDB(B0, 1, 0); PG8_LDB(B1, 1, 1); PG8_SCHED; PG8_LDA(At, 1, 0); PG8_STAGE(PG8_SA(0, 1), a2 + hstep, voffA);
;             PG8_WAIT_V(8); PG8_WAIT_L(0); PG8_BAR; PG8_MMA(0, 0, At, B0); PG8_MMA(0, 1, At, B1); PG8_BAR; PG8_SCHED;
	s_setprio 1
	s_waitcnt lgkmcnt(0)
	v_mfma_f32_16x16x32_bf16 v[64:67], v[132:135], v[192:195], v[64:67]
	v_mfma_f32_16x16x32_bf16 v[60:63], v[140:143], v[192:195], v[60:63]
	v_mfma_f32_16x16x32_bf16 v[48:51], v[132:135], v[200:203], v[48:51]
	v_mfma_f32_16x16x32_bf16 v[44:47], v[140:143], v[200:203], v[44:47]
	v_mfma_f32_16x16x32_bf16 v[32:35], v[132:135], v[218:221], v[32:35]
	v_mfma_f32_16x16x32_bf16 v[28:31], v[140:143], v[218:221], v[28:31]
	v_mfma_f32_16x16x32_bf16 v[16:19], v[132:135], v[226:229], v[16:19]
	v_mfma_f32_16x16x32_bf16 v[12:15], v[140:143], v[226:229], v[12:15]
	v_mfma_f32_16x16x32_bf16 v[64:67], v[136:139], v[196:199], v[64:67]
	v_mfma_f32_16x16x32_bf16 v[60:63], v[144:147], v[196:199], v[60:63]
	v_mfma_f32_16x16x32_bf16 v[48:51], v[136:139], v[204:207], v[48:51]
	v_mfma_f32_16x16x32_bf16 v[44:47], v[144:147], v[204:207], v[44:47]
	v_mfma_f32_16x16x32_bf16 v[32:35], v[136:139], v[222:225], v[32:35]
	v_mfma_f32_16x16x32_bf16 v[28:31], v[144:147], v[222:225], v[28:31]
	v_mfma_f32_16x16x32_bf16 v[16:19], v[136:139], v[230:233], v[16:19]
	v_mfma_f32_16x16x32_bf16 v[12:15], v[144:147], v[230:233], v[12:15]
	v_mfma_f32_16x16x32_bf16 v[56:59], v[148:151], v[192:195], v[56:59]
	v_mfma_f32_16x16x32_bf16 v[52:55], v[184:187], v[192:195], v[52:55]
	v_mfma_f32_16x16x32_bf16 v[40:43], v[148:151], v[200:203], v[40:43]
	v_mfma_f32_16x16x32_bf16 v[36:39], v[184:187], v[200:203], v[36:39]
	v_mfma_f32_16x16x32_bf16 v[24:27], v[148:151], v[218:221], v[24:27]
	v_mfma_f32_16x16x32_bf16 v[20:23], v[184:187], v[218:221], v[20:23]
	v_mfma_f32_16x16x32_bf16 v[8:11], v[148:151], v[226:229], v[8:11]
	v_mfma_f32_16x16x32_bf16 v[2:5], v[184:187], v[226:229], v[4:7]
	v_mfma_f32_16x16x32_bf16 v[56:59], v[152:155], v[196:199], v[56:59]
	v_mfma_f32_16x16x32_bf16 v[52:55], v[188:191], v[196:199], v[52:55]
	v_mfma_f32_16x16x32_bf16 v[40:43], v[152:155], v[204:207], v[40:43]
	v_mfma_f32_16x16x32_bf16 v[36:39], v[188:191], v[204:207], v[36:39]
	v_mfma_f32_16x16x32_bf16 v[24:27], v[152:155], v[222:225], v[24:27]
	v_mfma_f32_16x16x32_bf16 v[20:23], v[188:191], v[222:225], v[20:23]
	v_mfma_f32_16x16x32_bf16 v[8:11], v[152:155], v[230:233], v[8:11]
	v_mfma_f32_16x16x32_bf16 v[2:5], v[188:191], v[230:233], v[2:5]
	s_setprio 0
	s_barrier
	s_add_i32 s34, 0, 0x18000
	v_add_u32_e32 v0, s34, v212
	s_add_i32 s35, 0, 0x1c000
	ds_read_b128 v[132:135], v0
	ds_read_b128 v[136:139], v0 offset:1024
	ds_read_b128 v[140:143], v0 offset:2048
	ds_read_b128 v[144:147], v0 offset:3072
	v_add_u32_e32 v0, s35, v212
	ds_read_b128 v[148:151], v0
	ds_read_b128 v[152:155], v0 offset:1024
	ds_read_b128 v[184:187], v0 offset:2048
	ds_read_b128 v[188:191], v0 offset:3072
	s_add_u32 s16, s16, 0x80000
	s_addc_u32 s17, s17, 0
	s_mov_b32 m0, s90
	v_lshl_add_u64 v[6:7], s[16:17], 0, v[156:157]
	ds_read_b128 v[192:195], v216 offset:32768
	ds_read_b128 v[196:199], v216 offset:33792
	ds_read_b128 v[200:203], v216 offset:34816
	ds_read_b128 v[204:207], v216 offset:35840
	ds_read_b128 v[218:221], v216 offset:36864
	ds_read_b128 v[222:225], v216 offset:37888
	ds_read_b128 v[226:229], v216 offset:38912
	ds_read_b128 v[230:233], v216 offset:39936
	global_load_lds_dwordx4 v[6:7], off
	v_lshl_add_u64 v[6:7], s[16:17], 0, v[160:161]
	s_mov_b32 m0, s91
	s_nop 0
	global_load_lds_dwordx4 v[6:7], off
	s_waitcnt vmcnt(8)
	s_waitcnt lgkmcnt(0)
	s_barrier
	s_setprio 1
	s_waitcnt lgkmcnt(0)
	v_mfma_f32_16x16x32_bf16 v[128:131], v[132:135], v[192:195], v[128:131]
	v_mfma_f32_16x16x32_bf16 v[124:127], v[140:143], v[192:195], v[124:127]
	v_mfma_f32_16x16x32_bf16 v[112:115], v[132:135], v[200:203], v[112:115]
	v_mfma_f32_16x16x32_bf16 v[108:111], v[140:143], v[200:203], v[108:111]
	v_mfma_f32_16x16x32_bf16 v[96:99], v[132:135], v[218:221], v[96:99]
	v_mfma_f32_16x16x32_bf16 v[92:95], v[140:143], v[218:221], v[92:95]
	v_mfma_f32_16x16x32_bf16 v[80:83], v[132:135], v[226:229], v[80:83]
	v_mfma_f32_16x16x32_bf16 v[76:79], v[140:143], v[226:229], v[76:79]
	v_mfma_f32_16x16x32_bf16 v[128:131], v[136:139], v[196:199], v[128:131]
	v_mfma_f32_16x16x32_bf16 v[124:127], v[144:147], v[196:199], v[124:127]
	v_mfma_f32_16x16x32_bf16 v[112:115], v[136:139], v[204:207], v[112:115]
	v_mfma_f32_16x16x32_bf16 v[108:111], v[144:147], v[204:207], v[108:111]
	v_mfma_f32_16x16x32_bf16 v[96:99], v[136:139], v[222:225], v[96:99]
	v_mfma_f32_16x16x32_bf16 v[92:95], v[144:147], v[222:225], v[92:95]
	v_mfma_f32_16x16x32_bf16 v[80:83], v[136:139], v[230:233], v[80:83]
	v_mfma_f32_16x16x32_bf16 v[76:79], v[144:147], v[230:233], v[76:79]
	v_mfma_f32_16x16x32_bf16 v[120:123], v[148:151], v[192:195], v[120:123]
	v_mfma_f32_16x16x32_bf16 v[116:119], v[184:187], v[192:195], v[116:119]
	v_mfma_f32_16x16x32_bf16 v[104:107], v[148:151], v[200:203], v[104:107]
	v_mfma_f32_16x16x32_bf16 v[100:103], v[184:187], v[200:203], v[100:103]
	v_mfma_f32_16x16x32_bf16 v[88:91], v[148:151], v[218:221], v[88:91]
	v_mfma_f32_16x16x32_bf16 v[84:87], v[184:187], v[218:221], v[84:87]
	v_mfma_f32_16x16x32_bf16 v[72:75], v[148:151], v[226:229], v[72:75]
	v_mfma_f32_16x16x32_bf16 v[68:71], v[184:187], v[226:229], v[68:71]
	v_mfma_f32_16x16x32_bf16 v[120:123], v[152:155], v[196:199], v[120:123]
	v_mfma_f32_16x16x32_bf16 v[116:119], v[188:191], v[196:199], v[116:119]
	v_mfma_f32_16x16x32_bf16 v[104:107], v[152:155], v[204:207], v[104:107]
	v_mfma_f32_16x16x32_bf16 v[100:103], v[188:191], v[204:207], v[100:103]
	v_mfma_f32_16x16x32_bf16 v[88:91], v[152:155], v[222:225], v[88:91]
	v_mfma_f32_16x16x32_bf16 v[84:87], v[188:191], v[222:225], v[84:87]
	v_mfma_f32_16x16x32_bf16 v[72:75], v[152:155], v[230:233], v[72:75]
	v_mfma_f32_16x16x32_bf16 v[68:71], v[188:191], v[230:233], v[68:71]
	s_setprio 0
	s_barrier
; #define PG8_STAGE(bufoff, gbase, voff) do { _Pragma("unroll") for (int _i = 0; _i < 2; ++_i) \
;         __builtin_amdgcn_global_load_lds((const __attribute__((address_space(1))) unsigned*)((const char*)(gbase) + (voff)[_i]), (LAS unsigned*)(lds + (bufoff) + ldsw + _i * 8192), 16, 0, 0); } while (0)
; #define PG8_LDA(dst, b, h) do { _Pragma("unroll") for (int m = 0; m < 4; ++m) _Pragma("unroll") for (int k = 0; k < 2; ++k) dst[m][k] = *(const LAS bf16x8*)(lds + PG8_SA(b, h) + aoff + m * 2048 + k * 1024); } while (0)
; #define PG8_MMA(ai, bj, At, Bt) do { __builtin_amdgcn_s_setprio(1); _Pragma("unroll") for (int m = 0; m < 4; ++m) _Pragma("unroll") for (int n = 0; n < 2; ++n) _Pragma("unroll") for (int k = 0; k < 2; ++k) \
;         acc[ai][bj][m][n] = __builtin_amdgcn_mfma_f32_16x16x32_bf16(Bt[n][k], At[m][k], acc[ai][bj][m][n], 0, 0, 0); __builtin_amdgcn_s_setprio(0); } while (0)
; #define PG8_WAIT_V(n) asm volatile("s_waitcnt vmcnt(" #n ")" ::: "memory")
; #define PG8_WAIT_L(n) asm volatile("s_waitcnt lgkmcnt(" #n ")" ::: "memory")
; #define PG8_BAR __builtin_amdgcn_s_barrier()
; #define PG8_SCHED __builtin_amdgcn_sched_barrier(0)
; template <class Epi, class SchedT, bool ALIGN_EPI, bool SP2>
; __device__ __forceinline__ void gemm_phase(LAS unsigned char* lds, const int ldk, const int nt, const SchedT& S, const Epi& E) {
;     ...
;         for (int t = 0; t < nt; t += 2) {
;     ...
;             PG8_LDA(At, 1, 1); PG8_STAGE(PG8_SB(1, 0), b3, voffB); PG8_STAGE(PG8_SB(1, 1), b3 + hstepB, voffB); PG8_STAGE(PG8_SA(1, 0), a3, voffA);
;             PG8_WAIT_V(8); PG8_WAIT_L(0); PG8_BAR; PG8_MMA(1, 0, At, B0); PG8_MMA(1, 1, At, B1); PG8_BAR; PG8_SCHED;
	s_add_i32 s16, s34, s87
	v_lshl_add_u64 v[6:7], v[208:209], 0, s[24:25]
	s_mov_b32 m0, s16
	ds_read_b128 v[192:195], v216 offset:49152
	ds_read_b128 v[196:199], v216 offset:50176
	ds_read_b128 v[200:203], v216 offset:51200
	ds_read_b128 v[204:207], v216 offset:52224
	ds_read_b128 v[218:221], v216 offset:53248
	ds_read_b128 v[222:225], v216 offset:54272
	ds_read_b128 v[226:229], v216 offset:55296
	ds_read_b128 v[230:233], v216 offset:56320
	global_load_lds_dwordx4 v[6:7], off
	s_add_i32 m0, s16, 0x2000
	s_add_u32 s12, s12, 0x20080
	v_lshl_add_u64 v[6:7], v[234:235], 0, s[24:25]
	s_addc_u32 s13, s13, 0
	s_add_i32 s16, s35, s87
	global_load_lds_dwordx4 v[6:7], off
	v_lshl_add_u64 v[6:7], s[12:13], 0, v[158:159]
	s_mov_b32 m0, s16
	s_nop 0
	global_load_lds_dwordx4 v[6:7], off
	v_lshl_add_u64 v[6:7], s[12:13], 0, v[174:175]
	s_add_i32 m0, s16, 0x2000
	s_nop 0
	global_load_lds_dwordx4 v[6:7], off
	v_lshl_add_u64 v[6:7], v[236:237], 0, s[24:25]
	s_mov_b32 m0, s92
	s_nop 0
	global_load_lds_dwordx4 v[6:7], off
	v_lshl_add_u64 v[6:7], v[238:239], 0, s[24:25]
	s_mov_b32 m0, s93
	s_nop 0
	global_load_lds_dwordx4 v[6:7], off
	s_waitcnt vmcnt(8)
	s_waitcnt lgkmcnt(0)
	s_barrier
	s_setprio 1
	s_waitcnt lgkmcnt(0)
	v_mfma_f32_16x16x32_bf16 v[64:67], v[132:135], v[192:195], v[64:67]
	v_mfma_f32_16x16x32_bf16 v[60:63], v[140:143], v[192:195], v[60:63]
	v_mfma_f32_16x16x32_bf16 v[48:51], v[132:135], v[200:203], v[48:51]
	v_mfma_f32_16x16x32_bf16 v[44:47], v[140:143], v[200:203], v[44:47]
	v_mfma_f32_16x16x32_bf16 v[32:35], v[132:135], v[218:221], v[32:35]
	v_mfma_f32_16x16x32_bf16 v[28:31], v[140:143], v[218:221], v[28:31]
	v_mfma_f32_16x16x32_bf16 v[16:19], v[132:135], v[226:229], v[16:19]
	v_mfma_f32_16x16x32_bf16 v[12:15], v[140:143], v[226:229], v[12:15]
	v_mfma_f32_16x16x32_bf16 v[64:67], v[136:139], v[196:199], v[64:67]
	v_mfma_f32_16x16x32_bf16 v[60:63], v[144:147], v[196:199], v[60:63]
	v_mfma_f32_16x16x32_bf16 v[48:51], v[136:139], v[204:207], v[48:51]
	v_mfma_f32_16x16x32_bf16 v[44:47], v[144:147], v[204:207], v[44:47]
	v_mfma_f32_16x16x32_bf16 v[32:35], v[136:139], v[222:225], v[32:35]
	v_mfma_f32_16x16x32_bf16 v[28:31], v[144:147], v[222:225], v[28:31]
	v_mfma_f32_16x16x32_bf16 v[16:19], v[136:139], v[230:233], v[16:19]
	v_mfma_f32_16x16x32_bf16 v[12:15], v[144:147], v[230:233], v[12:15]
	v_mfma_f32_16x16x32_bf16 v[56:59], v[148:151], v[192:195], v[56:59]
	v_mfma_f32_16x16x32_bf16 v[52:55], v[184:187], v[192:195], v[52:55]
	v_mfma_f32_16x16x32_bf16 v[40:43], v[148:151], v[200:203], v[40:43]
	v_mfma_f32_16x16x32_bf16 v[36:39], v[184:187], v[200:203], v[36:39]
	v_mfma_f32_16x16x32_bf16 v[24:27], v[148:151], v[218:221], v[24:27]
	v_mfma_f32_16x16x32_bf16 v[20:23], v[184:187], v[218:221], v[20:23]
	v_mfma_f32_16x16x32_bf16 v[6:9], v[148:151], v[226:229], v[8:11]
	v_mfma_f32_16x16x32_bf16 v[2:5], v[184:187], v[226:229], v[2:5]
	v_mfma_f32_16x16x32_bf16 v[56:59], v[152:155], v[196:199], v[56:59]
	v_mfma_f32_16x16x32_bf16 v[52:55], v[188:191], v[196:199], v[52:55]
	v_mfma_f32_16x16x32_bf16 v[40:43], v[152:155], v[204:207], v[40:43]
	v_mfma_f32_16x16x32_bf16 v[36:39], v[188:191], v[204:207], v[36:39]
	v_mfma_f32_16x16x32_bf16 v[24:27], v[152:155], v[222:225], v[24:27]
	v_mfma_f32_16x16x32_bf16 v[20:23], v[188:191], v[222:225], v[20:23]
	v_mfma_f32_16x16x32_bf16 v[8:11], v[152:155], v[230:233], v[6:9]
	v_mfma_f32_16x16x32_bf16 v[4:7], v[188:191], v[230:233], v[2:5]
	s_setprio 0
	s_barrier
	s_add_i32 s21, s21, 2
	s_add_u32 s0, s0, 0x100
	s_addc_u32 s1, s1, 0
	s_add_u32 s18, s18, 0x100
	s_addc_u32 s19, s19, 0
	s_cmp_gt_u32 s21, 29
	s_cbranch_scc0 .LBB0_123
	s_and_b64 vcc, exec, s[58:59]
	s_cbranch_vccz .LBB0_126
	s_barrier

; #define PG8_STAGE(bufoff, gbase, voff) do { _Pragma("unroll") for (int _i = 0; _i < 2; ++_i) \
;         __builtin_amdgcn_global_load_lds((const __attribute__((address_space(1))) unsigned*)((const char*)(gbase) + (voff)[_i]), (LAS unsigned*)(lds + (bufoff) + ldsw + _i * 8192), 16, 0, 0); } while (0)
; #define PG8_LDA(dst, b, h) do { _Pragma("unroll") for (int m = 0; m < 4; ++m) _Pragma("unroll") for (int k = 0; k < 2; ++k) dst[m][k] = *(const LAS bf16x8*)(lds + PG8_SA(b, h) + aoff + m * 2048 + k * 1024); } while (0)
; #define PG8_LDB(dst, b, h) do { _Pragma("unroll") for (int n = 0; n < 2; ++n) _Pragma("unroll") for (int k = 0; k < 2; ++k) dst[n][k] = *(const LAS bf16x8*)(lds + PG8_SB(b, h) + boff + n * 2048 + k * 1024); } while (0)
; #define PG8_MMA(ai, bj, At, Bt) do { __builtin_amdgcn_s_setprio(1); _Pragma("unroll") for (int m = 0; m < 4; ++m) _Pragma("unroll") for (int n = 0; n < 2; ++n) _Pragma("unroll") for (int k = 0; k < 2; ++k) \
;         acc[ai][bj][m][n] = __builtin_amdgcn_mfma_f32_16x16x32_bf16(Bt[n][k], At[m][k], acc[ai][bj][m][n], 0, 0, 0); __builtin_amdgcn_s_setprio(0); } while (0)
; #define PG8_WAIT_V(n) asm volatile("s_waitcnt vmcnt(" #n ")" ::: "memory")
; #define PG8_WAIT_L(n) asm volatile("s_waitcnt lgkmcnt(" #n ")" ::: "memory")
; #define PG8_BAR __builtin_amdgcn_s_barrier()
; #define PG8_SCHED __builtin_amdgcn_sched_barrier(0)
; template <class Epi, class SchedT, bool ALIGN_EPI, bool SP2>
; __device__ __forceinline__ void gemm_phase(LAS unsigned char* lds, const int ldk, const int nt, const SchedT& S, const Epi& E) {
;     ...
;             PG8_LDB(B0, 0, 0); PG8_LDB(B1, 0, 1); PG8_SCHED; PG8_LDA(At, 0, 0); PG8_STAGE(PG8_SA(1, 1), a1 + hstep, voffA);
;             PG8_WAIT_V(8); PG8_WAIT_L(0); PG8_BAR; PG8_MMA(0, 0, At, B0); PG8_MMA(0, 1, At, B1); PG8_BAR; PG8_SCHED;
;             PG8_LDA(At, 0, 1); PG8_STAGE(PG8_SB(0, 0), b2, voffB); PG8_STAGE(PG8_SB(0, 1), b2 + hstepB, voffB); PG8_STAGE(PG8_SA(0, 0), a2, voffA);
;             PG8_WAIT_V(8); PG8_WAIT_L(0); PG8_BAR; PG8_MMA(1, 0, At, B0); PG8_MMA(1, 1, At, B1); PG8_BAR; PG8_SCHED;
.LBB0_534:
	s_add_u32 s36, s34, 0xfff80080
	s_addc_u32 s37, s35, -1
	s_add_i32 s49, 0, 0x10000
	s_cmp_eq_u32 s47, 12
	s_cselect_b32 s41, s1, s37
	s_cselect_b32 s40, s0, s36
	v_add_u32_e32 v0, s49, v159
	s_cselect_b32 s37, s53, s20
	s_cselect_b32 s36, s52, s17
	s_add_i32 s51, 0, 0x14000
	ds_read_b128 v[144:147], v0
	ds_read_b128 v[148:151], v0 offset:1024
	ds_read_b128 v[152:155], v0 offset:2048
	ds_read_b128 v[174:177], v0 offset:3072
	v_add_u32_e32 v0, s51, v159
	ds_read_b128 v[178:181], v0
	ds_read_b128 v[182:185], v0 offset:1024
	ds_read_b128 v[186:189], v0 offset:2048
	ds_read_b128 v[190:193], v0 offset:3072
	v_lshl_add_u64 v[2:3], s[34:35], 0, v[140:141]
	s_add_i32 m0, s57, 0xc000
	ds_read_b128 v[194:197], v161
	ds_read_b128 v[198:201], v161 offset:1024
	ds_read_b128 v[202:205], v161 offset:2048
	ds_read_b128 v[206:209], v161 offset:3072
	ds_read_b128 v[210:213], v161 offset:4096
	ds_read_b128 v[214:217], v161 offset:5120
	ds_read_b128 v[218:221], v161 offset:6144
	ds_read_b128 v[222:225], v161 offset:7168
	global_load_lds_dwordx4 v[2:3], off
	v_lshl_add_u64 v[2:3], s[34:35], 0, v[142:143]
	s_add_i32 m0, s57, 0xe000
	s_nop 0
	global_load_lds_dwordx4 v[2:3], off
	s_waitcnt vmcnt(8)
	s_waitcnt lgkmcnt(0)
	s_barrier
	s_setprio 1
	s_waitcnt lgkmcnt(0)
	v_mfma_f32_16x16x32_bf16 v[128:131], v[144:147], v[194:197], v[128:131]
	v_mfma_f32_16x16x32_bf16 v[124:127], v[152:155], v[194:197], v[124:127]
	v_mfma_f32_16x16x32_bf16 v[120:123], v[144:147], v[202:205], v[120:123]
	v_mfma_f32_16x16x32_bf16 v[116:119], v[152:155], v[202:205], v[116:119]
	v_mfma_f32_16x16x32_bf16 v[112:115], v[144:147], v[210:213], v[112:115]
	v_mfma_f32_16x16x32_bf16 v[108:111], v[152:155], v[210:213], v[108:111]
	v_mfma_f32_16x16x32_bf16 v[104:107], v[144:147], v[218:221], v[104:107]
	v_mfma_f32_16x16x32_bf16 v[100:103], v[152:155], v[218:221], v[100:103]
	v_mfma_f32_16x16x32_bf16 v[128:131], v[148:151], v[198:201], v[128:131]
	v_mfma_f32_16x16x32_bf16 v[124:127], v[174:177], v[198:201], v[124:127]
	v_mfma_f32_16x16x32_bf16 v[120:123], v[148:151], v[206:209], v[120:123]
	v_mfma_f32_16x16x32_bf16 v[116:119], v[174:177], v[206:209], v[116:119]
	v_mfma_f32_16x16x32_bf16 v[112:115], v[148:151], v[214:217], v[112:115]
	v_mfma_f32_16x16x32_bf16 v[108:111], v[174:177], v[214:217], v[108:111]
	v_mfma_f32_16x16x32_bf16 v[104:107], v[148:151], v[222:225], v[104:107]
	v_mfma_f32_16x16x32_bf16 v[100:103], v[174:177], v[222:225], v[100:103]
	v_mfma_f32_16x16x32_bf16 v[96:99], v[178:181], v[194:197], v[96:99]
	v_mfma_f32_16x16x32_bf16 v[92:95], v[186:189], v[194:197], v[92:95]
	v_mfma_f32_16x16x32_bf16 v[88:91], v[178:181], v[202:205], v[88:91]
	v_mfma_f32_16x16x32_bf16 v[84:87], v[186:189], v[202:205], v[84:87]
	v_mfma_f32_16x16x32_bf16 v[80:83], v[178:181], v[210:213], v[80:83]
	v_mfma_f32_16x16x32_bf16 v[76:79], v[186:189], v[210:213], v[76:79]
	v_mfma_f32_16x16x32_bf16 v[72:75], v[178:181], v[218:221], v[72:75]
	v_mfma_f32_16x16x32_bf16 v[68:71], v[186:189], v[218:221], v[68:71]
	v_mfma_f32_16x16x32_bf16 v[96:99], v[182:185], v[198:201], v[96:99]
	v_mfma_f32_16x16x32_bf16 v[92:95], v[190:193], v[198:201], v[92:95]
	v_mfma_f32_16x16x32_bf16 v[88:91], v[182:185], v[206:209], v[88:91]
	v_mfma_f32_16x16x32_bf16 v[84:87], v[190:193], v[206:209], v[84:87]
	v_mfma_f32_16x16x32_bf16 v[80:83], v[182:185], v[214:217], v[80:83]
	v_mfma_f32_16x16x32_bf16 v[76:79], v[190:193], v[214:217], v[76:79]
	v_mfma_f32_16x16x32_bf16 v[72:75], v[182:185], v[222:225], v[72:75]
	v_mfma_f32_16x16x32_bf16 v[68:71], v[190:193], v[222:225], v[68:71]
	s_setprio 0
	s_barrier
	s_add_i32 s49, s49, s56
	v_lshl_add_u64 v[156:157], s[36:37], 0, v[134:135]
	s_mov_b32 m0, s49
	ds_read_b128 v[194:197], v161 offset:16384
	ds_read_b128 v[198:201], v161 offset:17408
	ds_read_b128 v[202:205], v161 offset:18432
	ds_read_b128 v[206:209], v161 offset:19456
	ds_read_b128 v[210:213], v161 offset:20480
	ds_read_b128 v[214:217], v161 offset:21504
	ds_read_b128 v[218:221], v161 offset:22528
	ds_read_b128 v[222:225], v161 offset:23552
	global_load_lds_dwordx4 v[156:157], off
	s_add_i32 m0, s49, 0x2000
	s_add_u32 s82, s36, 0x20000
	v_lshl_add_u64 v[226:227], s[36:37], 0, v[138:139]
	s_addc_u32 s83, s37, 0
	s_add_i32 s49, s51, s56
	global_load_lds_dwordx4 v[226:227], off
	v_lshl_add_u64 v[2:3], s[82:83], 0, v[134:135]
	s_mov_b32 m0, s49
	v_lshl_add_u64 v[228:229], s[40:41], 0, v[132:133]
	global_load_lds_dwordx4 v[2:3], off
	v_lshl_add_u64 v[2:3], s[82:83], 0, v[138:139]
	s_add_i32 m0, s49, 0x2000
	v_lshl_add_u64 v[230:231], s[40:41], 0, v[136:137]
	global_load_lds_dwordx4 v[2:3], off
	s_mov_b32 m0, s57
	s_nop 0
	global_load_lds_dwordx4 v[228:229], off
	s_mov_b32 m0, s58
	s_nop 0
	global_load_lds_dwordx4 v[230:231], off
	s_waitcnt vmcnt(8)
	s_waitcnt lgkmcnt(0)
	s_barrier
; #define PG8_STAGE(bufoff, gbase, voff) do { _Pragma("unroll") for (int _i = 0; _i < 2; ++_i) \
;         __builtin_amdgcn_global_load_lds((const __attribute__((address_space(1))) unsigned*)((const char*)(gbase) + (voff)[_i]), (LAS unsigned*)(lds + (bufoff) + ldsw + _i * 8192), 16, 0, 0); } while (0)
; #define PG8_LDA(dst, b, h) do { _Pragma("unroll") for (int m = 0; m < 4; ++m) _Pragma("unroll") for (int k = 0; k < 2; ++k) dst[m][k] = *(const LAS bf16x8*)(lds + PG8_SA(b, h) + aoff + m * 2048 + k * 1024); } while (0)
; #define PG8_LDB(dst, b, h) do { _Pragma("unroll") for (int n = 0; n < 2; ++n) _Pragma("unroll") for (int k = 0; k < 2; ++k) dst[n][k] = *(const LAS bf16x8*)(lds + PG8_SB(b, h) + boff + n * 2048 + k * 1024); } while (0)
; #define PG8_MMA(ai, bj, At, Bt) do { __builtin_amdgcn_s_setprio(1); _Pragma("unroll") for (int m = 0; m < 4; ++m) _Pragma("unroll") for (int n = 0; n < 2; ++n) _Pragma("unroll") for (int k = 0; k < 2; ++k) \
;         acc[ai][bj][m][n] = __builtin_amdgcn_mfma_f32_16x16x32_bf16(Bt[n][k], At[m][k], acc[ai][bj][m][n], 0, 0, 0); __builtin_amdgcn_s_setprio(0); } while (0)
; #define PG8_WAIT_V(n) asm volatile("s_waitcnt vmcnt(" #n ")" ::: "memory")
; #define PG8_WAIT_L(n) asm volatile("s_waitcnt lgkmcnt(" #n ")" ::: "memory")
; #define PG8_BAR __builtin_amdgcn_s_barrier()
; #define PG8_SCHED __builtin_amdgcn_sched_barrier(0)
; template <class Epi, class SchedT, bool ALIGN_EPI, bool SP2>
; __device__ __forceinline__ void gemm_phase(LAS unsigned char* lds, const int ldk, const int nt, const SchedT& S, const Epi& E) {
;     ...
;             PG8_WAIT_V(8); PG8_WAIT_L(0); PG8_BAR; PG8_MMA(1, 0, At, B0); PG8_MMA(1, 1, At, B1); PG8_BAR; PG8_SCHED;
;             PG8_LDB(B0, 1, 0); PG8_LDB(B1, 1, 1); PG8_SCHED; PG8_LDA(At, 1, 0); PG8_STAGE(PG8_SA(0, 1), a2 + hstep, voffA);
;             PG8_WAIT_V(8); PG8_WAIT_L(0); PG8_BAR; PG8_MMA(0, 0, At, B0); PG8_MMA(0, 1, At, B1); PG8_BAR; PG8_SCHED;
	s_setprio 1
	s_waitcnt lgkmcnt(0)
	v_mfma_f32_16x16x32_bf16 v[64:67], v[144:147], v[194:197], v[64:67]
	v_mfma_f32_16x16x32_bf16 v[60:63], v[152:155], v[194:197], v[60:63]
	v_mfma_f32_16x16x32_bf16 v[56:59], v[144:147], v[202:205], v[56:59]
	v_mfma_f32_16x16x32_bf16 v[52:55], v[152:155], v[202:205], v[52:55]
	v_mfma_f32_16x16x32_bf16 v[48:51], v[144:147], v[210:213], v[48:51]
	v_mfma_f32_16x16x32_bf16 v[44:47], v[152:155], v[210:213], v[44:47]
	v_mfma_f32_16x16x32_bf16 v[40:43], v[144:147], v[218:221], v[40:43]
	v_mfma_f32_16x16x32_bf16 v[36:39], v[152:155], v[218:221], v[36:39]
	v_mfma_f32_16x16x32_bf16 v[64:67], v[148:151], v[198:201], v[64:67]
	v_mfma_f32_16x16x32_bf16 v[60:63], v[174:177], v[198:201], v[60:63]
	v_mfma_f32_16x16x32_bf16 v[56:59], v[148:151], v[206:209], v[56:59]
	v_mfma_f32_16x16x32_bf16 v[52:55], v[174:177], v[206:209], v[52:55]
	v_mfma_f32_16x16x32_bf16 v[48:51], v[148:151], v[214:217], v[48:51]
	v_mfma_f32_16x16x32_bf16 v[44:47], v[174:177], v[214:217], v[44:47]
	v_mfma_f32_16x16x32_bf16 v[40:43], v[148:151], v[222:225], v[40:43]
	v_mfma_f32_16x16x32_bf16 v[36:39], v[174:177], v[222:225], v[36:39]
	v_mfma_f32_16x16x32_bf16 v[32:35], v[178:181], v[194:197], v[32:35]
	v_mfma_f32_16x16x32_bf16 v[28:31], v[186:189], v[194:197], v[28:31]
	v_mfma_f32_16x16x32_bf16 v[24:27], v[178:181], v[202:205], v[24:27]
	v_mfma_f32_16x16x32_bf16 v[20:23], v[186:189], v[202:205], v[20:23]
	v_mfma_f32_16x16x32_bf16 v[16:19], v[178:181], v[210:213], v[16:19]
	v_mfma_f32_16x16x32_bf16 v[12:15], v[186:189], v[210:213], v[12:15]
	v_mfma_f32_16x16x32_bf16 v[8:11], v[178:181], v[218:221], v[8:11]
	v_mfma_f32_16x16x32_bf16 v[2:5], v[186:189], v[218:221], v[4:7]
	v_mfma_f32_16x16x32_bf16 v[32:35], v[182:185], v[198:201], v[32:35]
	v_mfma_f32_16x16x32_bf16 v[28:31], v[190:193], v[198:201], v[28:31]
	v_mfma_f32_16x16x32_bf16 v[24:27], v[182:185], v[206:209], v[24:27]
	v_mfma_f32_16x16x32_bf16 v[20:23], v[190:193], v[206:209], v[20:23]
	v_mfma_f32_16x16x32_bf16 v[16:19], v[182:185], v[214:217], v[16:19]
	v_mfma_f32_16x16x32_bf16 v[12:15], v[190:193], v[214:217], v[12:15]
	v_mfma_f32_16x16x32_bf16 v[8:11], v[182:185], v[222:225], v[8:11]
	v_mfma_f32_16x16x32_bf16 v[2:5], v[190:193], v[222:225], v[2:5]
	s_setprio 0
	s_barrier
	s_add_i32 s49, 0, 0x18000
	v_add_u32_e32 v0, s49, v159
	s_add_i32 s51, 0, 0x1c000
	ds_read_b128 v[144:147], v0
	ds_read_b128 v[148:151], v0 offset:1024
	ds_read_b128 v[152:155], v0 offset:2048
	ds_read_b128 v[174:177], v0 offset:3072
	v_add_u32_e32 v0, s51, v159
	ds_read_b128 v[178:181], v0
	ds_read_b128 v[182:185], v0 offset:1024
	ds_read_b128 v[186:189], v0 offset:2048
	ds_read_b128 v[190:193], v0 offset:3072
	s_add_u32 s40, s40, 0x80000
	s_addc_u32 s41, s41, 0
	s_mov_b32 m0, s59
	v_lshl_add_u64 v[6:7], s[40:41], 0, v[132:133]
	ds_read_b128 v[194:197], v161 offset:32768
	ds_read_b128 v[198:201], v161 offset:33792
	ds_read_b128 v[202:205], v161 offset:34816
	ds_read_b128 v[206:209], v161 offset:35840
	ds_read_b128 v[210:213], v161 offset:36864
	ds_read_b128 v[214:217], v161 offset:37888
	ds_read_b128 v[218:221], v161 offset:38912
	ds_read_b128 v[222:225], v161 offset:39936
	global_load_lds_dwordx4 v[6:7], off
	v_lshl_add_u64 v[6:7], s[40:41], 0, v[136:137]
	s_mov_b32 m0, s60
	s_nop 0
	global_load_lds_dwordx4 v[6:7], off
	s_waitcnt vmcnt(8)
	s_waitcnt lgkmcnt(0)
	s_barrier
	s_setprio 1
	s_waitcnt lgkmcnt(0)
	v_mfma_f32_16x16x32_bf16 v[128:131], v[144:147], v[194:197], v[128:131]
	v_mfma_f32_16x16x32_bf16 v[124:127], v[152:155], v[194:197], v[124:127]
	v_mfma_f32_16x16x32_bf16 v[120:123], v[144:147], v[202:205], v[120:123]
	v_mfma_f32_16x16x32_bf16 v[116:119], v[152:155], v[202:205], v[116:119]
	v_mfma_f32_16x16x32_bf16 v[112:115], v[144:147], v[210:213], v[112:115]
	v_mfma_f32_16x16x32_bf16 v[108:111], v[152:155], v[210:213], v[108:111]
	v_mfma_f32_16x16x32_bf16 v[104:107], v[144:147], v[218:221], v[104:107]
	v_mfma_f32_16x16x32_bf16 v[100:103], v[152:155], v[218:221], v[100:103]
	v_mfma_f32_16x16x32_bf16 v[128:131], v[148:151], v[198:201], v[128:131]
	v_mfma_f32_16x16x32_bf16 v[124:127], v[174:177], v[198:201], v[124:127]
	v_mfma_f32_16x16x32_bf16 v[120:123], v[148:151], v[206:209], v[120:123]
	v_mfma_f32_16x16x32_bf16 v[116:119], v[174:177], v[206:209], v[116:119]
	v_mfma_f32_16x16x32_bf16 v[112:115], v[148:151], v[214:217], v[112:115]
	v_mfma_f32_16x16x32_bf16 v[108:111], v[174:177], v[214:217], v[108:111]
	v_mfma_f32_16x16x32_bf16 v[104:107], v[148:151], v[222:225], v[104:107]
	v_mfma_f32_16x16x32_bf16 v[100:103], v[174:177], v[222:225], v[100:103]
	v_mfma_f32_16x16x32_bf16 v[96:99], v[178:181], v[194:197], v[96:99]
	v_mfma_f32_16x16x32_bf16 v[92:95], v[186:189], v[194:197], v[92:95]
	v_mfma_f32_16x16x32_bf16 v[88:91], v[178:181], v[202:205], v[88:91]
	v_mfma_f32_16x16x32_bf16 v[84:87], v[186:189], v[202:205], v[84:87]
	v_mfma_f32_16x16x32_bf16 v[80:83], v[178:181], v[210:213], v[80:83]
	v_mfma_f32_16x16x32_bf16 v[76:79], v[186:189], v[210:213], v[76:79]
	v_mfma_f32_16x16x32_bf16 v[72:75], v[178:181], v[218:221], v[72:75]
	v_mfma_f32_16x16x32_bf16 v[68:71], v[186:189], v[218:221], v[68:71]
	v_mfma_f32_16x16x32_bf16 v[96:99], v[182:185], v[198:201], v[96:99]
	v_mfma_f32_16x16x32_bf16 v[92:95], v[190:193], v[198:201], v[92:95]
	v_mfma_f32_16x16x32_bf16 v[88:91], v[182:185], v[206:209], v[88:91]
	v_mfma_f32_16x16x32_bf16 v[84:87], v[190:193], v[206:209], v[84:87]
	v_mfma_f32_16x16x32_bf16 v[80:83], v[182:185], v[214:217], v[80:83]
	v_mfma_f32_16x16x32_bf16 v[76:79], v[190:193], v[214:217], v[76:79]
	v_mfma_f32_16x16x32_bf16 v[72:75], v[182:185], v[222:225], v[72:75]
	v_mfma_f32_16x16x32_bf16 v[68:71], v[190:193], v[222:225], v[68:71]
	s_setprio 0
	s_barrier
; #define PG8_STAGE(bufoff, gbase, voff) do { _Pragma("unroll") for (int _i = 0; _i < 2; ++_i) \
;         __builtin_amdgcn_global_load_lds((const __attribute__((address_space(1))) unsigned*)((const char*)(gbase) + (voff)[_i]), (LAS unsigned*)(lds + (bufoff) + ldsw + _i * 8192), 16, 0, 0); } while (0)
; #define PG8_LDA(dst, b, h) do { _Pragma("unroll") for (int m = 0; m < 4; ++m) _Pragma("unroll") for (int k = 0; k < 2; ++k) dst[m][k] = *(const LAS bf16x8*)(lds + PG8_SA(b, h) + aoff + m * 2048 + k * 1024); } while (0)
; #define PG8_MMA(ai, bj, At, Bt) do { __builtin_amdgcn_s_setprio(1); _Pragma("unroll") for (int m = 0; m < 4; ++m) _Pragma("unroll") for (int n = 0; n < 2; ++n) _Pragma("unroll") for (int k = 0; k < 2; ++k) \
;         acc[ai][bj][m][n] = __builtin_amdgcn_mfma_f32_16x16x32_bf16(Bt[n][k], At[m][k], acc[ai][bj][m][n], 0, 0, 0); __builtin_amdgcn_s_setprio(0); } while (0)
; #define PG8_WAIT_V(n) asm volatile("s_waitcnt vmcnt(" #n ")" ::: "memory")
; #define PG8_WAIT_L(n) asm volatile("s_waitcnt lgkmcnt(" #n ")" ::: "memory")
; template <class Epi, class SchedT, bool ALIGN_EPI, bool SP2>
; __device__ __forceinline__ void gemm_phase(LAS unsigned char* lds, const int ldk, const int nt, const SchedT& S, const Epi& E) {
;     ...
;             PG8_LDA(At, 1, 1); PG8_STAGE(PG8_SB(1, 0), b3, voffB); PG8_STAGE(PG8_SB(1, 1), b3 + hstepB, voffB); PG8_STAGE(PG8_SA(1, 0), a3, voffA);
;             PG8_WAIT_V(8); PG8_WAIT_L(0); PG8_BAR; PG8_MMA(1, 0, At, B0); PG8_MMA(1, 1, At, B1); PG8_BAR; PG8_SCHED;
;     __device__ __forceinline__ void operator()(f32x4 (&acc)[2][2][4][2], const Unit& u, int wr, int wc, int fr, int fq) const {
;         const int row0 = u.pm * BM + wr * 64 + fr, col0 = u.pn * BM + wc * 64 + 8 * fq;
; #pragma unroll
;         for (int ai = 0; ai < 2; ++ai)
; #pragma unroll
;             for (int m = 0; m < 4; ++m) {
;                 const int row = row0 + ai * HALF + m * 16;
; #pragma unroll
;                 for (int bj = 0; bj < 2; ++bj) {
;                     const int col = col0 + bj * 32;
;                     const unsigned char* grow = (const unsigned char*)Gt + (size_t)row * 4096 + col;
;                     const u32x2 gw = *(const u32x2*)(grow + 2048);
;                     f32x4 g0 = gate_d4(gw.x), g1 = gate_d4(gw.y);
;                     if (u.kind == 0) {
;                         const u32x2 aw = *(const u32x2*)grow;
	s_add_i32 s40, s49, s56
	v_lshl_add_u64 v[6:7], v[156:157], 0, s[24:25]
	s_mov_b32 m0, s40
	ds_read_b128 v[194:197], v161 offset:49152
	ds_read_b128 v[198:201], v161 offset:50176
	ds_read_b128 v[202:205], v161 offset:51200
	ds_read_b128 v[206:209], v161 offset:52224
	ds_read_b128 v[210:213], v161 offset:53248
	ds_read_b128 v[214:217], v161 offset:54272
	ds_read_b128 v[218:221], v161 offset:55296
	ds_read_b128 v[222:225], v161 offset:56320
	global_load_lds_dwordx4 v[6:7], off
	s_add_i32 m0, s40, 0x2000
	s_add_u32 s36, s36, 0x20080
	v_lshl_add_u64 v[6:7], v[226:227], 0, s[24:25]
	s_addc_u32 s37, s37, 0
	s_add_i32 s40, s51, s56
	global_load_lds_dwordx4 v[6:7], off
	v_lshl_add_u64 v[6:7], s[36:37], 0, v[134:135]
	s_mov_b32 m0, s40
	s_nop 0
	global_load_lds_dwordx4 v[6:7], off
	v_lshl_add_u64 v[6:7], s[36:37], 0, v[138:139]
	s_add_i32 m0, s40, 0x2000
	s_nop 0
	global_load_lds_dwordx4 v[6:7], off
	v_lshl_add_u64 v[6:7], v[228:229], 0, s[24:25]
	s_mov_b32 m0, s61
	s_nop 0
	global_load_lds_dwordx4 v[6:7], off
	v_lshl_add_u64 v[6:7], v[230:231], 0, s[24:25]
	s_mov_b32 m0, s62
	s_nop 0
	global_load_lds_dwordx4 v[6:7], off
	s_waitcnt vmcnt(8)
	s_waitcnt lgkmcnt(0)
	s_barrier
	s_setprio 1
	s_waitcnt lgkmcnt(0)
	v_mfma_f32_16x16x32_bf16 v[64:67], v[144:147], v[194:197], v[64:67]
	v_mfma_f32_16x16x32_bf16 v[60:63], v[152:155], v[194:197], v[60:63]
	v_mfma_f32_16x16x32_bf16 v[56:59], v[144:147], v[202:205], v[56:59]
	v_mfma_f32_16x16x32_bf16 v[52:55], v[152:155], v[202:205], v[52:55]
	v_mfma_f32_16x16x32_bf16 v[48:51], v[144:147], v[210:213], v[48:51]
	v_mfma_f32_16x16x32_bf16 v[44:47], v[152:155], v[210:213], v[44:47]
	v_mfma_f32_16x16x32_bf16 v[40:43], v[144:147], v[218:221], v[40:43]
	v_mfma_f32_16x16x32_bf16 v[36:39], v[152:155], v[218:221], v[36:39]
	v_mfma_f32_16x16x32_bf16 v[64:67], v[148:151], v[198:201], v[64:67]
	v_mfma_f32_16x16x32_bf16 v[60:63], v[174:177], v[198:201], v[60:63]
	v_mfma_f32_16x16x32_bf16 v[56:59], v[148:151], v[206:209], v[56:59]
	v_mfma_f32_16x16x32_bf16 v[52:55], v[174:177], v[206:209], v[52:55]
	v_mfma_f32_16x16x32_bf16 v[48:51], v[148:151], v[214:217], v[48:51]
	v_mfma_f32_16x16x32_bf16 v[44:47], v[174:177], v[214:217], v[44:47]
	v_mfma_f32_16x16x32_bf16 v[40:43], v[148:151], v[222:225], v[40:43]
	v_mfma_f32_16x16x32_bf16 v[36:39], v[174:177], v[222:225], v[36:39]
	v_mfma_f32_16x16x32_bf16 v[32:35], v[178:181], v[194:197], v[32:35]
	v_mfma_f32_16x16x32_bf16 v[28:31], v[186:189], v[194:197], v[28:31]
	v_mfma_f32_16x16x32_bf16 v[24:27], v[178:181], v[202:205], v[24:27]
	v_mfma_f32_16x16x32_bf16 v[20:23], v[186:189], v[202:205], v[20:23]
	v_mfma_f32_16x16x32_bf16 v[16:19], v[178:181], v[210:213], v[16:19]
	v_mfma_f32_16x16x32_bf16 v[12:15], v[186:189], v[210:213], v[12:15]
	v_mfma_f32_16x16x32_bf16 v[6:9], v[178:181], v[218:221], v[8:11]
	v_mfma_f32_16x16x32_bf16 v[2:5], v[186:189], v[218:221], v[2:5]
	v_mfma_f32_16x16x32_bf16 v[32:35], v[182:185], v[198:201], v[32:35]
	v_mfma_f32_16x16x32_bf16 v[28:31], v[190:193], v[198:201], v[28:31]
	v_mfma_f32_16x16x32_bf16 v[24:27], v[182:185], v[206:209], v[24:27]
	v_mfma_f32_16x16x32_bf16 v[20:23], v[190:193], v[206:209], v[20:23]
	v_mfma_f32_16x16x32_bf16 v[16:19], v[182:185], v[214:217], v[16:19]
	v_mfma_f32_16x16x32_bf16 v[12:15], v[190:193], v[214:217], v[12:15]
	v_mfma_f32_16x16x32_bf16 v[8:11], v[182:185], v[222:225], v[6:9]
	v_mfma_f32_16x16x32_bf16 v[4:7], v[190:193], v[222:225], v[2:5]
	s_setprio 0
	s_barrier
	s_add_i32 s47, s47, 2
	s_add_u32 s34, s34, 0x100
	s_addc_u32 s35, s35, 0
	s_add_u32 s17, s17, 0x100
	s_addc_u32 s20, s20, 0
	s_cmp_gt_u32 s47, 13
	s_cbranch_scc0 .LBB0_534
	v_lshl_add_u32 v144, s16, 8, v158
	v_lshl_or_b32 v145, s12, 8, v160
	v_lshl_add_u32 v146, v144, 12, v145
	v_add_u32_e32 v147, 0x10000, v146
	v_add_u32_e32 v148, 0x20000, v146
	v_add_u32_e32 v149, 0x30000, v146
	v_add_u32_e32 v150, 0x80000, v146
	v_add_u32_e32 v151, 0x90000, v146
	v_add_u32_e32 v152, 0xa0000, v146
	v_add_u32_e32 v153, 0xb0000, v146
	s_cmp_lg_u32 s13, 0
	s_cbranch_scc1 .Lp3e_k1_loads
	global_load_dwordx2 v[174:175], v146, s[30:31] offset:2048
	global_load_dwordx2 v[176:177], v146, s[30:31] offset:0
	global_load_dwordx2 v[178:179], v146, s[30:31] offset:2080
	global_load_dwordx2 v[180:181], v146, s[30:31] offset:32
	global_load_dwordx2 v[182:183], v147, s[30:31] offset:2048
	global_load_dwordx2 v[184:185], v147, s[30:31] offset:0
	global_load_dwordx2 v[186:187], v147, s[30:31] offset:2080
	global_load_dwordx2 v[188:189], v147, s[30:31] offset:32
	global_load_dwordx2 v[190:191], v148, s[30:31] offset:2048
	global_load_dwordx2 v[192:193], v148, s[30:31] offset:0
	global_load_dwordx2 v[194:195], v148, s[30:31] offset:2080
	global_load_dwordx2 v[196:197], v148, s[30:31] offset:32
	global_load_dwordx2 v[198:199], v149, s[30:31] offset:2048
	global_load_dwordx2 v[200:201], v149, s[30:31] offset:0
	global_load_dwordx2 v[202:203], v149, s[30:31] offset:2080
	global_load_dwordx2 v[204:205], v149, s[30:31] offset:32
	global_load_dwordx2 v[206:207], v150, s[30:31] offset:2048
	global_load_dwordx2 v[208:209], v150, s[30:31] offset:0
	global_load_dwordx2 v[210:211], v150, s[30:31] offset:2080
	global_load_dwordx2 v[212:213], v150, s[30:31] offset:32
	global_load_dwordx2 v[214:215], v151, s[30:31] offset:2048
	global_load_dwordx2 v[216:217], v151, s[30:31] offset:0
	global_load_dwordx2 v[218:219], v151, s[30:31] offset:2080
	global_load_dwordx2 v[220:221], v151, s[30:31] offset:32
	global_load_dwordx2 v[222:223], v152, s[30:31] offset:2048
	global_load_dwordx2 v[224:225], v152, s[30:31] offset:0
	global_load_dwordx2 v[226:227], v152, s[30:31] offset:2080
	global_load_dwordx2 v[228:229], v152, s[30:31] offset:32
	global_load_dwordx2 v[230:231], v153, s[30:31] offset:2048
	global_load_dwordx2 v[232:233], v153, s[30:31] offset:0
	global_load_dwordx2 v[234:235], v153, s[30:31] offset:2080
	global_load_dwordx2 v[236:237], v153, s[30:31] offset:32
	s_branch .Lp3e_align

; #define PG8_STAGE(bufoff, gbase, voff) do { _Pragma("unroll") for (int _i = 0; _i < 2; ++_i) \
;         __builtin_amdgcn_global_load_lds((const __attribute__((address_space(1))) unsigned*)((const char*)(gbase) + (voff)[_i]), (LAS unsigned*)(lds + (bufoff) + ldsw + _i * 8192), 16, 0, 0); } while (0)
; #define PG8_LDA(dst, b, h) do { _Pragma("unroll") for (int m = 0; m < 4; ++m) _Pragma("unroll") for (int k = 0; k < 2; ++k) dst[m][k] = *(const LAS bf16x8*)(lds + PG8_SA(b, h) + aoff + m * 2048 + k * 1024); } while (0)
; #define PG8_LDB(dst, b, h) do { _Pragma("unroll") for (int n = 0; n < 2; ++n) _Pragma("unroll") for (int k = 0; k < 2; ++k) dst[n][k] = *(const LAS bf16x8*)(lds + PG8_SB(b, h) + boff + n * 2048 + k * 1024); } while (0)
; #define PG8_MMA(ai, bj, At, Bt) do { __builtin_amdgcn_s_setprio(1); _Pragma("unroll") for (int m = 0; m < 4; ++m) _Pragma("unroll") for (int n = 0; n < 2; ++n) _Pragma("unroll") for (int k = 0; k < 2; ++k) \
;         acc[ai][bj][m][n] = __builtin_amdgcn_mfma_f32_16x16x32_bf16(Bt[n][k], At[m][k], acc[ai][bj][m][n], 0, 0, 0); __builtin_amdgcn_s_setprio(0); } while (0)
; #define PG8_WAIT_V(n) asm volatile("s_waitcnt vmcnt(" #n ")" ::: "memory")
; #define PG8_WAIT_L(n) asm volatile("s_waitcnt lgkmcnt(" #n ")" ::: "memory")
; #define PG8_BAR __builtin_amdgcn_s_barrier()
; #define PG8_SCHED __builtin_amdgcn_sched_barrier(0)
; template <class Epi, class SchedT, bool ALIGN_EPI, bool SP2>
; __device__ __forceinline__ void gemm_phase(LAS unsigned char* lds, const int ldk, const int nt, const SchedT& S, const Epi& E) {
;     ...
;             PG8_LDB(B0, 0, 0); PG8_LDB(B1, 0, 1); PG8_SCHED; PG8_LDA(At, 0, 0); PG8_STAGE(PG8_SA(1, 1), a1 + hstep, voffA);
;             PG8_WAIT_V(8); PG8_WAIT_L(0); PG8_BAR; PG8_MMA(0, 0, At, B0); PG8_MMA(0, 1, At, B1); PG8_BAR; PG8_SCHED;
;             PG8_LDA(At, 0, 1); PG8_STAGE(PG8_SB(0, 0), b2, voffB); PG8_STAGE(PG8_SB(0, 1), b2 + hstepB, voffB); PG8_STAGE(PG8_SA(0, 0), a2, voffA);
;             PG8_WAIT_V(8); PG8_WAIT_L(0); PG8_BAR; PG8_MMA(1, 0, At, B0); PG8_MMA(1, 1, At, B1); PG8_BAR; PG8_SCHED;
.LBB0_668:
	s_add_u32 s36, s34, 0xfff80080
	s_addc_u32 s37, s35, -1
	s_add_i32 s51, 0, 0x10000
	s_cmp_eq_u32 s22, 28
	s_cselect_b32 s57, s1, s37
	s_cselect_b32 s56, s0, s36
	v_add_u32_e32 v144, s51, v147
	s_cselect_b32 s37, s55, s20
	s_cselect_b32 s36, s54, s13
	s_add_i32 s53, 0, 0x14000
	ds_read_b128 v[140:143], v144
	ds_read_b128 v[150:153], v144 offset:1024
	ds_read_b128 v[154:157], v144 offset:2048
	ds_read_b128 v[158:161], v144 offset:3072
	v_add_u32_e32 v144, s53, v147
	ds_read_b128 v[174:177], v144
	ds_read_b128 v[178:181], v144 offset:1024
	ds_read_b128 v[182:185], v144 offset:2048
	ds_read_b128 v[186:189], v144 offset:3072
	v_lshl_add_u64 v[144:145], s[34:35], 0, v[136:137]
	s_add_i32 m0, s17, 0xc000
	ds_read_b128 v[190:193], v149
	ds_read_b128 v[194:197], v149 offset:1024
	ds_read_b128 v[198:201], v149 offset:2048
	ds_read_b128 v[202:205], v149 offset:3072
	ds_read_b128 v[206:209], v149 offset:4096
	ds_read_b128 v[210:213], v149 offset:5120
	ds_read_b128 v[214:217], v149 offset:6144
	ds_read_b128 v[218:221], v149 offset:7168
	global_load_lds_dwordx4 v[144:145], off
	v_lshl_add_u64 v[144:145], s[34:35], 0, v[138:139]
	s_add_i32 m0, s17, 0xe000
	s_nop 0
	global_load_lds_dwordx4 v[144:145], off
	s_waitcnt vmcnt(8)
	s_waitcnt lgkmcnt(0)
	s_barrier
	s_setprio 1
	s_waitcnt lgkmcnt(0)
	v_mfma_f32_16x16x32_bf16 v[126:129], v[140:143], v[190:193], v[126:129]
	v_mfma_f32_16x16x32_bf16 v[122:125], v[154:157], v[190:193], v[122:125]
	v_mfma_f32_16x16x32_bf16 v[110:113], v[140:143], v[198:201], v[110:113]
	v_mfma_f32_16x16x32_bf16 v[106:109], v[154:157], v[198:201], v[106:109]
	v_mfma_f32_16x16x32_bf16 v[94:97], v[140:143], v[206:209], v[94:97]
	v_mfma_f32_16x16x32_bf16 v[90:93], v[154:157], v[206:209], v[90:93]
	v_mfma_f32_16x16x32_bf16 v[78:81], v[140:143], v[214:217], v[78:81]
	v_mfma_f32_16x16x32_bf16 v[74:77], v[154:157], v[214:217], v[74:77]
	v_mfma_f32_16x16x32_bf16 v[126:129], v[150:153], v[194:197], v[126:129]
	v_mfma_f32_16x16x32_bf16 v[122:125], v[158:161], v[194:197], v[122:125]
	v_mfma_f32_16x16x32_bf16 v[110:113], v[150:153], v[202:205], v[110:113]
	v_mfma_f32_16x16x32_bf16 v[106:109], v[158:161], v[202:205], v[106:109]
	v_mfma_f32_16x16x32_bf16 v[94:97], v[150:153], v[210:213], v[94:97]
	v_mfma_f32_16x16x32_bf16 v[90:93], v[158:161], v[210:213], v[90:93]
	v_mfma_f32_16x16x32_bf16 v[78:81], v[150:153], v[218:221], v[78:81]
	v_mfma_f32_16x16x32_bf16 v[74:77], v[158:161], v[218:221], v[74:77]
	v_mfma_f32_16x16x32_bf16 v[118:121], v[174:177], v[190:193], v[118:121]
	v_mfma_f32_16x16x32_bf16 v[114:117], v[182:185], v[190:193], v[114:117]
	v_mfma_f32_16x16x32_bf16 v[102:105], v[174:177], v[198:201], v[102:105]
	v_mfma_f32_16x16x32_bf16 v[98:101], v[182:185], v[198:201], v[98:101]
	v_mfma_f32_16x16x32_bf16 v[86:89], v[174:177], v[206:209], v[86:89]
	v_mfma_f32_16x16x32_bf16 v[82:85], v[182:185], v[206:209], v[82:85]
	v_mfma_f32_16x16x32_bf16 v[70:73], v[174:177], v[214:217], v[70:73]
	v_mfma_f32_16x16x32_bf16 v[66:69], v[182:185], v[214:217], v[66:69]
	v_mfma_f32_16x16x32_bf16 v[118:121], v[178:181], v[194:197], v[118:121]
	v_mfma_f32_16x16x32_bf16 v[114:117], v[186:189], v[194:197], v[114:117]
	v_mfma_f32_16x16x32_bf16 v[102:105], v[178:181], v[202:205], v[102:105]
	v_mfma_f32_16x16x32_bf16 v[98:101], v[186:189], v[202:205], v[98:101]
	v_mfma_f32_16x16x32_bf16 v[86:89], v[178:181], v[210:213], v[86:89]
	v_mfma_f32_16x16x32_bf16 v[82:85], v[186:189], v[210:213], v[82:85]
	v_mfma_f32_16x16x32_bf16 v[70:73], v[178:181], v[218:221], v[70:73]
	v_mfma_f32_16x16x32_bf16 v[66:69], v[186:189], v[218:221], v[66:69]
	s_setprio 0
	s_barrier
	s_add_i32 s51, s51, s61
	v_lshl_add_u64 v[144:145], s[36:37], 0, v[0:1]
	s_mov_b32 m0, s51
	ds_read_b128 v[190:193], v149 offset:16384
	ds_read_b128 v[194:197], v149 offset:17408
	ds_read_b128 v[198:201], v149 offset:18432
	ds_read_b128 v[202:205], v149 offset:19456
	ds_read_b128 v[206:209], v149 offset:20480
	ds_read_b128 v[210:213], v149 offset:21504
	ds_read_b128 v[214:217], v149 offset:22528
	ds_read_b128 v[218:221], v149 offset:23552
	global_load_lds_dwordx4 v[144:145], off
	s_add_i32 m0, s51, 0x2000
	s_add_u32 s86, s36, 0x20000
	v_lshl_add_u64 v[222:223], s[36:37], 0, v[134:135]
	s_addc_u32 s87, s37, 0
	s_add_i32 s51, s53, s61
	global_load_lds_dwordx4 v[222:223], off
	v_lshl_add_u64 v[224:225], s[86:87], 0, v[0:1]
	s_mov_b32 m0, s51
	v_lshl_add_u64 v[226:227], s[56:57], 0, v[132:133]
	global_load_lds_dwordx4 v[224:225], off
	v_lshl_add_u64 v[224:225], s[86:87], 0, v[134:135]
	s_add_i32 m0, s51, 0x2000
	s_nop 0
	global_load_lds_dwordx4 v[224:225], off
	v_lshl_add_u64 v[224:225], s[56:57], 0, v[130:131]
	s_mov_b32 m0, s17
	s_nop 0
	global_load_lds_dwordx4 v[224:225], off
	s_mov_b32 m0, s62
	s_nop 0
	global_load_lds_dwordx4 v[226:227], off
	s_waitcnt vmcnt(8)
	s_waitcnt lgkmcnt(0)
	s_barrier
; #define PG8_STAGE(bufoff, gbase, voff) do { _Pragma("unroll") for (int _i = 0; _i < 2; ++_i) \
;         __builtin_amdgcn_global_load_lds((const __attribute__((address_space(1))) unsigned*)((const char*)(gbase) + (voff)[_i]), (LAS unsigned*)(lds + (bufoff) + ldsw + _i * 8192), 16, 0, 0); } while (0)
; #define PG8_LDA(dst, b, h) do { _Pragma("unroll") for (int m = 0; m < 4; ++m) _Pragma("unroll") for (int k = 0; k < 2; ++k) dst[m][k] = *(const LAS bf16x8*)(lds + PG8_SA(b, h) + aoff + m * 2048 + k * 1024); } while (0)
; #define PG8_LDB(dst, b, h) do { _Pragma("unroll") for (int n = 0; n < 2; ++n) _Pragma("unroll") for (int k = 0; k < 2; ++k) dst[n][k] = *(const LAS bf16x8*)(lds + PG8_SB(b, h) + boff + n * 2048 + k * 1024); } while (0)
; #define PG8_MMA(ai, bj, At, Bt) do { __builtin_amdgcn_s_setprio(1); _Pragma("unroll") for (int m = 0; m < 4; ++m) _Pragma("unroll") for (int n = 0; n < 2; ++n) _Pragma("unroll") for (int k = 0; k < 2; ++k) \
;         acc[ai][bj][m][n] = __builtin_amdgcn_mfma_f32_16x16x32_bf16(Bt[n][k], At[m][k], acc[ai][bj][m][n], 0, 0, 0); __builtin_amdgcn_s_setprio(0); } while (0)
; #define PG8_WAIT_V(n) asm volatile("s_waitcnt vmcnt(" #n ")" ::: "memory")
; #define PG8_WAIT_L(n) asm volatile("s_waitcnt lgkmcnt(" #n ")" ::: "memory")
; #define PG8_BAR __builtin_amdgcn_s_barrier()
; #define PG8_SCHED __builtin_amdgcn_sched_barrier(0)
; template <class Epi, class SchedT, bool ALIGN_EPI, bool SP2>
; __device__ __forceinline__ void gemm_phase(LAS unsigned char* lds, const int ldk, const int nt, const SchedT& S, const Epi& E) {
;     ...
;             PG8_WAIT_V(8); PG8_WAIT_L(0); PG8_BAR; PG8_MMA(1, 0, At, B0); PG8_MMA(1, 1, At, B1); PG8_BAR; PG8_SCHED;
;             PG8_LDB(B0, 1, 0); PG8_LDB(B1, 1, 1); PG8_SCHED; PG8_LDA(At, 1, 0); PG8_STAGE(PG8_SA(0, 1), a2 + hstep, voffA);
;             PG8_WAIT_V(8); PG8_WAIT_L(0); PG8_BAR; PG8_MMA(0, 0, At, B0); PG8_MMA(0, 1, At, B1); PG8_BAR; PG8_SCHED;
	s_setprio 1
	s_waitcnt lgkmcnt(0)
	v_mfma_f32_16x16x32_bf16 v[62:65], v[140:143], v[190:193], v[62:65]
	v_mfma_f32_16x16x32_bf16 v[58:61], v[154:157], v[190:193], v[58:61]
	v_mfma_f32_16x16x32_bf16 v[46:49], v[140:143], v[198:201], v[46:49]
	v_mfma_f32_16x16x32_bf16 v[42:45], v[154:157], v[198:201], v[42:45]
	v_mfma_f32_16x16x32_bf16 v[30:33], v[140:143], v[206:209], v[30:33]
	v_mfma_f32_16x16x32_bf16 v[26:29], v[154:157], v[206:209], v[26:29]
	v_mfma_f32_16x16x32_bf16 v[14:17], v[140:143], v[214:217], v[14:17]
	v_mfma_f32_16x16x32_bf16 v[10:13], v[154:157], v[214:217], v[10:13]
	v_mfma_f32_16x16x32_bf16 v[62:65], v[150:153], v[194:197], v[62:65]
	v_mfma_f32_16x16x32_bf16 v[58:61], v[158:161], v[194:197], v[58:61]
	v_mfma_f32_16x16x32_bf16 v[46:49], v[150:153], v[202:205], v[46:49]
	v_mfma_f32_16x16x32_bf16 v[42:45], v[158:161], v[202:205], v[42:45]
	v_mfma_f32_16x16x32_bf16 v[30:33], v[150:153], v[210:213], v[30:33]
	v_mfma_f32_16x16x32_bf16 v[26:29], v[158:161], v[210:213], v[26:29]
	v_mfma_f32_16x16x32_bf16 v[14:17], v[150:153], v[218:221], v[14:17]
	v_mfma_f32_16x16x32_bf16 v[10:13], v[158:161], v[218:221], v[10:13]
	v_mfma_f32_16x16x32_bf16 v[54:57], v[174:177], v[190:193], v[54:57]
	v_mfma_f32_16x16x32_bf16 v[50:53], v[182:185], v[190:193], v[50:53]
	v_mfma_f32_16x16x32_bf16 v[38:41], v[174:177], v[198:201], v[38:41]
	v_mfma_f32_16x16x32_bf16 v[34:37], v[182:185], v[198:201], v[34:37]
	v_mfma_f32_16x16x32_bf16 v[22:25], v[174:177], v[206:209], v[22:25]
	v_mfma_f32_16x16x32_bf16 v[18:21], v[182:185], v[206:209], v[18:21]
	v_mfma_f32_16x16x32_bf16 v[6:9], v[174:177], v[214:217], v[6:9]
	v_mfma_f32_16x16x32_bf16 v[2:5], v[182:185], v[214:217], v[2:5]
	v_mfma_f32_16x16x32_bf16 v[54:57], v[178:181], v[194:197], v[54:57]
	v_mfma_f32_16x16x32_bf16 v[50:53], v[186:189], v[194:197], v[50:53]
	v_mfma_f32_16x16x32_bf16 v[38:41], v[178:181], v[202:205], v[38:41]
	v_mfma_f32_16x16x32_bf16 v[34:37], v[186:189], v[202:205], v[34:37]
	v_mfma_f32_16x16x32_bf16 v[22:25], v[178:181], v[210:213], v[22:25]
	v_mfma_f32_16x16x32_bf16 v[18:21], v[186:189], v[210:213], v[18:21]
	v_mfma_f32_16x16x32_bf16 v[6:9], v[178:181], v[218:221], v[6:9]
	v_mfma_f32_16x16x32_bf16 v[2:5], v[186:189], v[218:221], v[2:5]
	s_setprio 0
	s_barrier
	s_add_i32 s51, 0, 0x18000
	s_add_i32 s53, 0, 0x1c000
	v_add_u32_e32 v158, s51, v147
	v_add_u32_e32 v186, s53, v147
	ds_read_b128 v[140:143], v158
	ds_read_b128 v[150:153], v158 offset:1024
	ds_read_b128 v[154:157], v158 offset:2048
	ds_read_b128 v[158:161], v158 offset:3072
	ds_read_b128 v[174:177], v186
	ds_read_b128 v[178:181], v186 offset:1024
	ds_read_b128 v[182:185], v186 offset:2048
	ds_read_b128 v[186:189], v186 offset:3072
	s_add_u32 s56, s56, 0x80000
	s_addc_u32 s57, s57, 0
	s_mov_b32 m0, s63
	v_lshl_add_u64 v[228:229], s[56:57], 0, v[130:131]
	ds_read_b128 v[190:193], v149 offset:32768
	ds_read_b128 v[194:197], v149 offset:33792
	ds_read_b128 v[198:201], v149 offset:34816
	ds_read_b128 v[202:205], v149 offset:35840
	ds_read_b128 v[206:209], v149 offset:36864
	ds_read_b128 v[210:213], v149 offset:37888
	ds_read_b128 v[214:217], v149 offset:38912
	ds_read_b128 v[218:221], v149 offset:39936
	global_load_lds_dwordx4 v[228:229], off
	v_lshl_add_u64 v[228:229], s[56:57], 0, v[132:133]
	s_mov_b32 m0, s81
	s_nop 0
	global_load_lds_dwordx4 v[228:229], off
	s_waitcnt vmcnt(8)
	s_waitcnt lgkmcnt(0)
	s_barrier
	s_setprio 1
	s_waitcnt lgkmcnt(0)
	v_mfma_f32_16x16x32_bf16 v[126:129], v[140:143], v[190:193], v[126:129]
	v_mfma_f32_16x16x32_bf16 v[122:125], v[154:157], v[190:193], v[122:125]
	v_mfma_f32_16x16x32_bf16 v[110:113], v[140:143], v[198:201], v[110:113]
	v_mfma_f32_16x16x32_bf16 v[106:109], v[154:157], v[198:201], v[106:109]
	v_mfma_f32_16x16x32_bf16 v[94:97], v[140:143], v[206:209], v[94:97]
	v_mfma_f32_16x16x32_bf16 v[90:93], v[154:157], v[206:209], v[90:93]
	v_mfma_f32_16x16x32_bf16 v[78:81], v[140:143], v[214:217], v[78:81]
	v_mfma_f32_16x16x32_bf16 v[74:77], v[154:157], v[214:217], v[74:77]
	v_mfma_f32_16x16x32_bf16 v[126:129], v[150:153], v[194:197], v[126:129]
	v_mfma_f32_16x16x32_bf16 v[122:125], v[158:161], v[194:197], v[122:125]
	v_mfma_f32_16x16x32_bf16 v[110:113], v[150:153], v[202:205], v[110:113]
	v_mfma_f32_16x16x32_bf16 v[106:109], v[158:161], v[202:205], v[106:109]
	v_mfma_f32_16x16x32_bf16 v[94:97], v[150:153], v[210:213], v[94:97]
	v_mfma_f32_16x16x32_bf16 v[90:93], v[158:161], v[210:213], v[90:93]
	v_mfma_f32_16x16x32_bf16 v[78:81], v[150:153], v[218:221], v[78:81]
	v_mfma_f32_16x16x32_bf16 v[74:77], v[158:161], v[218:221], v[74:77]
	v_mfma_f32_16x16x32_bf16 v[118:121], v[174:177], v[190:193], v[118:121]
	v_mfma_f32_16x16x32_bf16 v[114:117], v[182:185], v[190:193], v[114:117]
	v_mfma_f32_16x16x32_bf16 v[102:105], v[174:177], v[198:201], v[102:105]
	v_mfma_f32_16x16x32_bf16 v[98:101], v[182:185], v[198:201], v[98:101]
	v_mfma_f32_16x16x32_bf16 v[86:89], v[174:177], v[206:209], v[86:89]
	v_mfma_f32_16x16x32_bf16 v[82:85], v[182:185], v[206:209], v[82:85]
	v_mfma_f32_16x16x32_bf16 v[70:73], v[174:177], v[214:217], v[70:73]
	v_mfma_f32_16x16x32_bf16 v[66:69], v[182:185], v[214:217], v[66:69]
	v_mfma_f32_16x16x32_bf16 v[118:121], v[178:181], v[194:197], v[118:121]
	v_mfma_f32_16x16x32_bf16 v[114:117], v[186:189], v[194:197], v[114:117]
	v_mfma_f32_16x16x32_bf16 v[102:105], v[178:181], v[202:205], v[102:105]
	v_mfma_f32_16x16x32_bf16 v[98:101], v[186:189], v[202:205], v[98:101]
	v_mfma_f32_16x16x32_bf16 v[86:89], v[178:181], v[210:213], v[86:89]
	v_mfma_f32_16x16x32_bf16 v[82:85], v[186:189], v[210:213], v[82:85]
	v_mfma_f32_16x16x32_bf16 v[70:73], v[178:181], v[218:221], v[70:73]
	v_mfma_f32_16x16x32_bf16 v[66:69], v[186:189], v[218:221], v[66:69]
	s_setprio 0
	s_barrier
; #define PG8_STAGE(bufoff, gbase, voff) do { _Pragma("unroll") for (int _i = 0; _i < 2; ++_i) \
;         __builtin_amdgcn_global_load_lds((const __attribute__((address_space(1))) unsigned*)((const char*)(gbase) + (voff)[_i]), (LAS unsigned*)(lds + (bufoff) + ldsw + _i * 8192), 16, 0, 0); } while (0)
; #define PG8_LDA(dst, b, h) do { _Pragma("unroll") for (int m = 0; m < 4; ++m) _Pragma("unroll") for (int k = 0; k < 2; ++k) dst[m][k] = *(const LAS bf16x8*)(lds + PG8_SA(b, h) + aoff + m * 2048 + k * 1024); } while (0)
; #define PG8_MMA(ai, bj, At, Bt) do { __builtin_amdgcn_s_setprio(1); _Pragma("unroll") for (int m = 0; m < 4; ++m) _Pragma("unroll") for (int n = 0; n < 2; ++n) _Pragma("unroll") for (int k = 0; k < 2; ++k) \
;         acc[ai][bj][m][n] = __builtin_amdgcn_mfma_f32_16x16x32_bf16(Bt[n][k], At[m][k], acc[ai][bj][m][n], 0, 0, 0); __builtin_amdgcn_s_setprio(0); } while (0)
; #define PG8_WAIT_V(n) asm volatile("s_waitcnt vmcnt(" #n ")" ::: "memory")
; #define PG8_WAIT_L(n) asm volatile("s_waitcnt lgkmcnt(" #n ")" ::: "memory")
; #define PG8_BAR __builtin_amdgcn_s_barrier()
; #define PG8_SCHED __builtin_amdgcn_sched_barrier(0)
; template <class Epi, class SchedT, bool ALIGN_EPI, bool SP2>
; __device__ __forceinline__ void gemm_phase(LAS unsigned char* lds, const int ldk, const int nt, const SchedT& S, const Epi& E) {
;     ...
;             PG8_LDA(At, 1, 1); PG8_STAGE(PG8_SB(1, 0), b3, voffB); PG8_STAGE(PG8_SB(1, 1), b3 + hstepB, voffB); PG8_STAGE(PG8_SA(1, 0), a3, voffA);
;             PG8_WAIT_V(8); PG8_WAIT_L(0); PG8_BAR; PG8_MMA(1, 0, At, B0); PG8_MMA(1, 1, At, B1); PG8_BAR; PG8_SCHED;
;     __device__ __forceinline__ void operator()(f32x4 (&acc)[2][2][4][2], const Unit& u, int wr, int wc, int fr, int fq) const {
;         const int row0 = u.pm * BM + wr * 64 + fr, col0 = u.pn * BM + wc * 64 + 8 * fq;
; #pragma unroll
;         for (int ai = 0; ai < 2; ++ai)
; #pragma unroll
;             for (int m = 0; m < 4; ++m) {
;                 const int row = row0 + ai * HALF + m * 16; float sq = 0.f;
; #pragma unroll
;                 for (int bj = 0; bj < 2; ++bj) {
;                     const size_t off = (size_t)row * D + col0 + bj * 32;
;                     const u32x4 xw = *(const u32x4*)(xin + off);
	s_add_i32 s51, s51, s61
	v_lshl_add_u64 v[144:145], v[144:145], 0, s[24:25]
	s_mov_b32 m0, s51
	ds_read_b128 v[190:193], v149 offset:49152
	ds_read_b128 v[194:197], v149 offset:50176
	ds_read_b128 v[198:201], v149 offset:51200
	ds_read_b128 v[202:205], v149 offset:52224
	ds_read_b128 v[206:209], v149 offset:53248
	ds_read_b128 v[210:213], v149 offset:54272
	ds_read_b128 v[214:217], v149 offset:55296
	ds_read_b128 v[218:221], v149 offset:56320
	global_load_lds_dwordx4 v[144:145], off
	s_add_i32 m0, s51, 0x2000
	s_add_u32 s36, s36, 0x20080
	v_lshl_add_u64 v[144:145], v[222:223], 0, s[24:25]
	s_addc_u32 s37, s37, 0
	s_add_i32 s51, s53, s61
	global_load_lds_dwordx4 v[144:145], off
	v_lshl_add_u64 v[144:145], s[36:37], 0, v[0:1]
	s_mov_b32 m0, s51
	s_nop 0
	global_load_lds_dwordx4 v[144:145], off
	v_lshl_add_u64 v[144:145], s[36:37], 0, v[134:135]
	s_add_i32 m0, s51, 0x2000
	s_nop 0
	global_load_lds_dwordx4 v[144:145], off
	v_lshl_add_u64 v[144:145], v[224:225], 0, s[24:25]
	s_mov_b32 m0, s83
	s_nop 0
	global_load_lds_dwordx4 v[144:145], off
	v_lshl_add_u64 v[144:145], v[226:227], 0, s[24:25]
	s_mov_b32 m0, s84
	s_nop 0
	global_load_lds_dwordx4 v[144:145], off
	s_waitcnt vmcnt(8)
	s_waitcnt lgkmcnt(0)
	s_barrier
	s_setprio 1
	s_waitcnt lgkmcnt(0)
	v_mfma_f32_16x16x32_bf16 v[62:65], v[140:143], v[190:193], v[62:65]
	v_mfma_f32_16x16x32_bf16 v[58:61], v[154:157], v[190:193], v[58:61]
	v_mfma_f32_16x16x32_bf16 v[46:49], v[140:143], v[198:201], v[46:49]
	v_mfma_f32_16x16x32_bf16 v[42:45], v[154:157], v[198:201], v[42:45]
	v_mfma_f32_16x16x32_bf16 v[30:33], v[140:143], v[206:209], v[30:33]
	v_mfma_f32_16x16x32_bf16 v[26:29], v[154:157], v[206:209], v[26:29]
	v_mfma_f32_16x16x32_bf16 v[14:17], v[140:143], v[214:217], v[14:17]
	v_mfma_f32_16x16x32_bf16 v[10:13], v[154:157], v[214:217], v[10:13]
	v_mfma_f32_16x16x32_bf16 v[62:65], v[150:153], v[194:197], v[62:65]
	v_mfma_f32_16x16x32_bf16 v[58:61], v[158:161], v[194:197], v[58:61]
	v_mfma_f32_16x16x32_bf16 v[46:49], v[150:153], v[202:205], v[46:49]
	v_mfma_f32_16x16x32_bf16 v[42:45], v[158:161], v[202:205], v[42:45]
	v_mfma_f32_16x16x32_bf16 v[30:33], v[150:153], v[210:213], v[30:33]
	v_mfma_f32_16x16x32_bf16 v[26:29], v[158:161], v[210:213], v[26:29]
	v_mfma_f32_16x16x32_bf16 v[14:17], v[150:153], v[218:221], v[14:17]
	v_mfma_f32_16x16x32_bf16 v[10:13], v[158:161], v[218:221], v[10:13]
	v_mfma_f32_16x16x32_bf16 v[54:57], v[174:177], v[190:193], v[54:57]
	v_mfma_f32_16x16x32_bf16 v[50:53], v[182:185], v[190:193], v[50:53]
	v_mfma_f32_16x16x32_bf16 v[38:41], v[174:177], v[198:201], v[38:41]
	v_mfma_f32_16x16x32_bf16 v[34:37], v[182:185], v[198:201], v[34:37]
	v_mfma_f32_16x16x32_bf16 v[22:25], v[174:177], v[206:209], v[22:25]
	v_mfma_f32_16x16x32_bf16 v[18:21], v[182:185], v[206:209], v[18:21]
	v_mfma_f32_16x16x32_bf16 v[6:9], v[174:177], v[214:217], v[6:9]
	v_mfma_f32_16x16x32_bf16 v[2:5], v[182:185], v[214:217], v[2:5]
	v_mfma_f32_16x16x32_bf16 v[54:57], v[178:181], v[194:197], v[54:57]
	v_mfma_f32_16x16x32_bf16 v[50:53], v[186:189], v[194:197], v[50:53]
	v_mfma_f32_16x16x32_bf16 v[38:41], v[178:181], v[202:205], v[38:41]
	v_mfma_f32_16x16x32_bf16 v[34:37], v[186:189], v[202:205], v[34:37]
	v_mfma_f32_16x16x32_bf16 v[22:25], v[178:181], v[210:213], v[22:25]
	v_mfma_f32_16x16x32_bf16 v[18:21], v[186:189], v[210:213], v[18:21]
	v_mfma_f32_16x16x32_bf16 v[6:9], v[178:181], v[218:221], v[6:9]
	v_mfma_f32_16x16x32_bf16 v[2:5], v[186:189], v[218:221], v[2:5]
	s_setprio 0
	s_barrier
	s_add_i32 s22, s22, 2
	s_add_u32 s34, s34, 0x100
	s_addc_u32 s35, s35, 0
	s_add_u32 s13, s13, 0x100
	s_addc_u32 s20, s20, 0
	s_cmp_gt_u32 s22, 29
	s_cbranch_scc0 .LBB0_668
	v_lshl_add_u32 v142, s16, 8, v146
	v_lshl_or_b32 v140, s12, 8, v148
	v_lshlrev_b32_e32 v141, 12, v142
	v_lshl_add_u32 v150, v140, 1, v141
	v_add_u32_e32 v151, 0x10000, v150
	v_add_u32_e32 v152, 0x20000, v150
	v_add_u32_e32 v153, 0x30000, v150
	v_add_u32_e32 v154, 0x80000, v150
	v_add_u32_e32 v155, 0x90000, v150
	v_add_u32_e32 v156, 0xa0000, v150
	v_add_u32_e32 v157, 0xb0000, v150
	global_load_dwordx4 v[174:177], v150, s[42:43]
	global_load_dwordx4 v[178:181], v150, s[42:43] offset:64
	global_load_dwordx4 v[182:185], v151, s[42:43]
	global_load_dwordx4 v[186:189], v151, s[42:43] offset:64
	global_load_dwordx4 v[190:193], v152, s[42:43]
	global_load_dwordx4 v[194:197], v152, s[42:43] offset:64
	global_load_dwordx4 v[198:201], v153, s[42:43]
	global_load_dwordx4 v[202:205], v153, s[42:43] offset:64
	global_load_dwordx4 v[206:209], v154, s[42:43]
	global_load_dwordx4 v[210:213], v154, s[42:43] offset:64
	global_load_dwordx4 v[214:217], v155, s[42:43]
	global_load_dwordx4 v[218:221], v155, s[42:43] offset:64
	global_load_dwordx4 v[222:225], v156, s[42:43]
	global_load_dwordx4 v[226:229], v156, s[42:43] offset:64
	global_load_dwordx4 v[230:233], v157, s[42:43]
	global_load_dwordx4 v[234:237], v157, s[42:43] offset:64
	s_lshl_b32 s56, s12, 4
	s_lshl_b32 s22, s82, 2
	s_add_i32 s56, s56, s22
	v_lshl_add_u32 v158, v142, 7, s56
	v_add_u32_e32 v159, 0x1000, v158
	v_add_u32_e32 v160, 0x4000, v158
	v_add_u32_e32 v161, 0x5000, v158
	v_xor_b32_e32 v239, 16, v241
	v_xor_b32_e32 v252, 32, v241
	v_lshlrev_b32_e32 v239, 2, v239
	v_lshlrev_b32_e32 v252, 2, v252
	s_and_b64 vcc, exec, s[48:49]
	s_cbranch_vccz .LBB0_671
	s_barrier

; #define PG8_STAGE(bufoff, gbase, voff) do { _Pragma("unroll") for (int _i = 0; _i < 2; ++_i) \
;         __builtin_amdgcn_global_load_lds((const __attribute__((address_space(1))) unsigned*)((const char*)(gbase) + (voff)[_i]), (LAS unsigned*)(lds + (bufoff) + ldsw + _i * 8192), 16, 0, 0); } while (0)
; #define PG8_LDA(dst, b, h) do { _Pragma("unroll") for (int m = 0; m < 4; ++m) _Pragma("unroll") for (int k = 0; k < 2; ++k) dst[m][k] = *(const LAS bf16x8*)(lds + PG8_SA(b, h) + aoff + m * 2048 + k * 1024); } while (0)
; #define PG8_LDB(dst, b, h) do { _Pragma("unroll") for (int n = 0; n < 2; ++n) _Pragma("unroll") for (int k = 0; k < 2; ++k) dst[n][k] = *(const LAS bf16x8*)(lds + PG8_SB(b, h) + boff + n * 2048 + k * 1024); } while (0)
; #define PG8_MMA(ai, bj, At, Bt) do { __builtin_amdgcn_s_setprio(1); _Pragma("unroll") for (int m = 0; m < 4; ++m) _Pragma("unroll") for (int n = 0; n < 2; ++n) _Pragma("unroll") for (int k = 0; k < 2; ++k) \
;         acc[ai][bj][m][n] = __builtin_amdgcn_mfma_f32_16x16x32_bf16(Bt[n][k], At[m][k], acc[ai][bj][m][n], 0, 0, 0); __builtin_amdgcn_s_setprio(0); } while (0)
; #define PG8_WAIT_V(n) asm volatile("s_waitcnt vmcnt(" #n ")" ::: "memory")
; #define PG8_WAIT_L(n) asm volatile("s_waitcnt lgkmcnt(" #n ")" ::: "memory")
; #define PG8_BAR __builtin_amdgcn_s_barrier()
; #define PG8_SCHED __builtin_amdgcn_sched_barrier(0)
; template <class Epi, class SchedT, bool ALIGN_EPI, bool SP2>
; __device__ __forceinline__ void gemm_phase(LAS unsigned char* lds, const int ldk, const int nt, const SchedT& S, const Epi& E) {
;     ...
;             PG8_LDB(B0, 0, 0); PG8_LDB(B1, 0, 1); PG8_SCHED; PG8_LDA(At, 0, 0); PG8_STAGE(PG8_SA(1, 1), a1 + hstep, voffA);
;             PG8_WAIT_V(8); PG8_WAIT_L(0); PG8_BAR; PG8_MMA(0, 0, At, B0); PG8_MMA(0, 1, At, B1); PG8_BAR; PG8_SCHED;
;             PG8_LDA(At, 0, 1); PG8_STAGE(PG8_SB(0, 0), b2, voffB); PG8_STAGE(PG8_SB(0, 1), b2 + hstepB, voffB); PG8_STAGE(PG8_SA(0, 0), a2, voffA);
;             PG8_WAIT_V(8); PG8_WAIT_L(0); PG8_BAR; PG8_MMA(1, 0, At, B0); PG8_MMA(1, 1, At, B1); PG8_BAR; PG8_SCHED;
.LBB0_752:
	s_add_u32 s36, s34, 0xfff80080
	s_addc_u32 s37, s35, -1
	s_add_i32 s61, 0, 0x10000
	s_cmp_eq_u32 s59, 28
	s_cselect_b32 vcc_hi, s1, s37
	s_cselect_b32 vcc_lo, s0, s36
	s_cselect_b32 s37, s63, s17
	s_cselect_b32 s36, s62, s13
	s_add_i32 s64, 0, 0x14000
	v_add_u32_e32 v142, s61, v248
	v_add_u32_e32 v182, s64, v248
	ds_read_b128 v[130:133], v142
	ds_read_b128 v[134:137], v142 offset:1024
	ds_read_b128 v[138:141], v142 offset:2048
	ds_read_b128 v[142:145], v142 offset:3072
	ds_read_b128 v[158:161], v182
	ds_read_b128 v[174:177], v182 offset:1024
	ds_read_b128 v[178:181], v182 offset:2048
	ds_read_b128 v[182:185], v182 offset:3072
	v_lshl_add_u64 v[218:219], s[34:35], 0, v[154:155]
	s_add_i32 m0, s85, 0xc000
	ds_read_b128 v[186:189], v251
	ds_read_b128 v[190:193], v251 offset:1024
	ds_read_b128 v[194:197], v251 offset:2048
	ds_read_b128 v[198:201], v251 offset:3072
	ds_read_b128 v[202:205], v251 offset:4096
	ds_read_b128 v[206:209], v251 offset:5120
	ds_read_b128 v[210:213], v251 offset:6144
	ds_read_b128 v[214:217], v251 offset:7168
	global_load_lds_dwordx4 v[218:219], off
	v_lshl_add_u64 v[218:219], s[34:35], 0, v[156:157]
	s_add_i32 m0, s85, 0xe000
	s_nop 0
	global_load_lds_dwordx4 v[218:219], off
	s_waitcnt vmcnt(8)
	s_waitcnt lgkmcnt(0)
	s_barrier
	s_setprio 1
	s_waitcnt lgkmcnt(0)
	v_mfma_f32_16x16x32_bf16 v[126:129], v[130:133], v[186:189], v[126:129]
	v_mfma_f32_16x16x32_bf16 v[62:65], v[138:141], v[186:189], v[62:65]
	v_mfma_f32_16x16x32_bf16 v[118:121], v[130:133], v[194:197], v[118:121]
	v_mfma_f32_16x16x32_bf16 v[58:61], v[138:141], v[194:197], v[58:61]
	v_mfma_f32_16x16x32_bf16 v[110:113], v[130:133], v[202:205], v[110:113]
	v_mfma_f32_16x16x32_bf16 v[46:49], v[138:141], v[202:205], v[46:49]
	v_mfma_f32_16x16x32_bf16 v[106:109], v[130:133], v[210:213], v[106:109]
	v_mfma_f32_16x16x32_bf16 v[42:45], v[138:141], v[210:213], v[42:45]
	v_mfma_f32_16x16x32_bf16 v[126:129], v[134:137], v[190:193], v[126:129]
	v_mfma_f32_16x16x32_bf16 v[62:65], v[142:145], v[190:193], v[62:65]
	v_mfma_f32_16x16x32_bf16 v[118:121], v[134:137], v[198:201], v[118:121]
	v_mfma_f32_16x16x32_bf16 v[58:61], v[142:145], v[198:201], v[58:61]
	v_mfma_f32_16x16x32_bf16 v[110:113], v[134:137], v[206:209], v[110:113]
	v_mfma_f32_16x16x32_bf16 v[46:49], v[142:145], v[206:209], v[46:49]
	v_mfma_f32_16x16x32_bf16 v[106:109], v[134:137], v[214:217], v[106:109]
	v_mfma_f32_16x16x32_bf16 v[42:45], v[142:145], v[214:217], v[42:45]
	v_mfma_f32_16x16x32_bf16 v[122:125], v[158:161], v[186:189], v[122:125]
	v_mfma_f32_16x16x32_bf16 v[54:57], v[178:181], v[186:189], v[54:57]
	v_mfma_f32_16x16x32_bf16 v[114:117], v[158:161], v[194:197], v[114:117]
	v_mfma_f32_16x16x32_bf16 v[50:53], v[178:181], v[194:197], v[50:53]
	v_mfma_f32_16x16x32_bf16 v[102:105], v[158:161], v[202:205], v[102:105]
	v_mfma_f32_16x16x32_bf16 v[38:41], v[178:181], v[202:205], v[38:41]
	v_mfma_f32_16x16x32_bf16 v[98:101], v[158:161], v[210:213], v[98:101]
	v_mfma_f32_16x16x32_bf16 v[34:37], v[178:181], v[210:213], v[34:37]
	v_mfma_f32_16x16x32_bf16 v[122:125], v[174:177], v[190:193], v[122:125]
	v_mfma_f32_16x16x32_bf16 v[54:57], v[182:185], v[190:193], v[54:57]
	v_mfma_f32_16x16x32_bf16 v[114:117], v[174:177], v[198:201], v[114:117]
	v_mfma_f32_16x16x32_bf16 v[50:53], v[182:185], v[198:201], v[50:53]
	v_mfma_f32_16x16x32_bf16 v[102:105], v[174:177], v[206:209], v[102:105]
	v_mfma_f32_16x16x32_bf16 v[38:41], v[182:185], v[206:209], v[38:41]
	v_mfma_f32_16x16x32_bf16 v[98:101], v[174:177], v[214:217], v[98:101]
	v_mfma_f32_16x16x32_bf16 v[34:37], v[182:185], v[214:217], v[34:37]
	s_setprio 0
	s_barrier
	s_add_i32 s61, s61, s84
	v_lshl_add_u64 v[218:219], s[36:37], 0, v[0:1]
	s_mov_b32 m0, s61
	ds_read_b128 v[186:189], v251 offset:16384
	ds_read_b128 v[190:193], v251 offset:17408
	ds_read_b128 v[194:197], v251 offset:18432
	ds_read_b128 v[198:201], v251 offset:19456
	ds_read_b128 v[202:205], v251 offset:20480
	ds_read_b128 v[206:209], v251 offset:21504
	ds_read_b128 v[210:213], v251 offset:22528
	ds_read_b128 v[214:217], v251 offset:23552
	global_load_lds_dwordx4 v[218:219], off
	s_add_i32 m0, s61, 0x2000
	s_add_u32 s94, s36, 0x20000
	v_lshl_add_u64 v[220:221], s[36:37], 0, v[150:151]
	s_addc_u32 s95, s37, 0
	s_add_i32 s61, s64, s84
	global_load_lds_dwordx4 v[220:221], off
	v_lshl_add_u64 v[222:223], s[94:95], 0, v[0:1]
	s_mov_b32 m0, s61
	v_lshl_add_u64 v[224:225], vcc, 0, v[148:149]
	global_load_lds_dwordx4 v[222:223], off
	v_lshl_add_u64 v[222:223], s[94:95], 0, v[150:151]
	s_add_i32 m0, s61, 0x2000
	s_nop 0
	global_load_lds_dwordx4 v[222:223], off
	v_lshl_add_u64 v[222:223], vcc, 0, v[146:147]
	s_mov_b32 m0, s85
	s_nop 0
	global_load_lds_dwordx4 v[222:223], off
	s_mov_b32 m0, s86
	s_nop 0
	global_load_lds_dwordx4 v[224:225], off
	s_waitcnt vmcnt(8)
	s_waitcnt lgkmcnt(0)
	s_barrier
; #define PG8_STAGE(bufoff, gbase, voff) do { _Pragma("unroll") for (int _i = 0; _i < 2; ++_i) \
;         __builtin_amdgcn_global_load_lds((const __attribute__((address_space(1))) unsigned*)((const char*)(gbase) + (voff)[_i]), (LAS unsigned*)(lds + (bufoff) + ldsw + _i * 8192), 16, 0, 0); } while (0)
; #define PG8_LDA(dst, b, h) do { _Pragma("unroll") for (int m = 0; m < 4; ++m) _Pragma("unroll") for (int k = 0; k < 2; ++k) dst[m][k] = *(const LAS bf16x8*)(lds + PG8_SA(b, h) + aoff + m * 2048 + k * 1024); } while (0)
; #define PG8_LDB(dst, b, h) do { _Pragma("unroll") for (int n = 0; n < 2; ++n) _Pragma("unroll") for (int k = 0; k < 2; ++k) dst[n][k] = *(const LAS bf16x8*)(lds + PG8_SB(b, h) + boff + n * 2048 + k * 1024); } while (0)
; #define PG8_MMA(ai, bj, At, Bt) do { __builtin_amdgcn_s_setprio(1); _Pragma("unroll") for (int m = 0; m < 4; ++m) _Pragma("unroll") for (int n = 0; n < 2; ++n) _Pragma("unroll") for (int k = 0; k < 2; ++k) \
;         acc[ai][bj][m][n] = __builtin_amdgcn_mfma_f32_16x16x32_bf16(Bt[n][k], At[m][k], acc[ai][bj][m][n], 0, 0, 0); __builtin_amdgcn_s_setprio(0); } while (0)
; #define PG8_WAIT_V(n) asm volatile("s_waitcnt vmcnt(" #n ")" ::: "memory")
; #define PG8_WAIT_L(n) asm volatile("s_waitcnt lgkmcnt(" #n ")" ::: "memory")
; #define PG8_BAR __builtin_amdgcn_s_barrier()
; #define PG8_SCHED __builtin_amdgcn_sched_barrier(0)
; template <class Epi, class SchedT, bool ALIGN_EPI, bool SP2>
; __device__ __forceinline__ void gemm_phase(LAS unsigned char* lds, const int ldk, const int nt, const SchedT& S, const Epi& E) {
;     ...
;             PG8_WAIT_V(8); PG8_WAIT_L(0); PG8_BAR; PG8_MMA(1, 0, At, B0); PG8_MMA(1, 1, At, B1); PG8_BAR; PG8_SCHED;
;             PG8_LDB(B0, 1, 0); PG8_LDB(B1, 1, 1); PG8_SCHED; PG8_LDA(At, 1, 0); PG8_STAGE(PG8_SA(0, 1), a2 + hstep, voffA);
;             PG8_WAIT_V(8); PG8_WAIT_L(0); PG8_BAR; PG8_MMA(0, 0, At, B0); PG8_MMA(0, 1, At, B1); PG8_BAR; PG8_SCHED;
	s_setprio 1
	s_waitcnt lgkmcnt(0)
	v_mfma_f32_16x16x32_bf16 v[94:97], v[130:133], v[186:189], v[94:97]
	v_mfma_f32_16x16x32_bf16 v[30:33], v[138:141], v[186:189], v[30:33]
	v_mfma_f32_16x16x32_bf16 v[90:93], v[130:133], v[194:197], v[90:93]
	v_mfma_f32_16x16x32_bf16 v[26:29], v[138:141], v[194:197], v[26:29]
	v_mfma_f32_16x16x32_bf16 v[78:81], v[130:133], v[202:205], v[78:81]
	v_mfma_f32_16x16x32_bf16 v[14:17], v[138:141], v[202:205], v[14:17]
	v_mfma_f32_16x16x32_bf16 v[74:77], v[130:133], v[210:213], v[74:77]
	v_mfma_f32_16x16x32_bf16 v[10:13], v[138:141], v[210:213], v[10:13]
	v_mfma_f32_16x16x32_bf16 v[94:97], v[134:137], v[190:193], v[94:97]
	v_mfma_f32_16x16x32_bf16 v[30:33], v[142:145], v[190:193], v[30:33]
	v_mfma_f32_16x16x32_bf16 v[90:93], v[134:137], v[198:201], v[90:93]
	v_mfma_f32_16x16x32_bf16 v[26:29], v[142:145], v[198:201], v[26:29]
	v_mfma_f32_16x16x32_bf16 v[78:81], v[134:137], v[206:209], v[78:81]
	v_mfma_f32_16x16x32_bf16 v[14:17], v[142:145], v[206:209], v[14:17]
	v_mfma_f32_16x16x32_bf16 v[74:77], v[134:137], v[214:217], v[74:77]
	v_mfma_f32_16x16x32_bf16 v[10:13], v[142:145], v[214:217], v[10:13]
	v_mfma_f32_16x16x32_bf16 v[86:89], v[158:161], v[186:189], v[86:89]
	v_mfma_f32_16x16x32_bf16 v[22:25], v[178:181], v[186:189], v[22:25]
	v_mfma_f32_16x16x32_bf16 v[82:85], v[158:161], v[194:197], v[82:85]
	v_mfma_f32_16x16x32_bf16 v[18:21], v[178:181], v[194:197], v[18:21]
	v_mfma_f32_16x16x32_bf16 v[70:73], v[158:161], v[202:205], v[70:73]
	v_mfma_f32_16x16x32_bf16 v[6:9], v[178:181], v[202:205], v[6:9]
	v_mfma_f32_16x16x32_bf16 v[66:69], v[158:161], v[210:213], v[66:69]
	v_mfma_f32_16x16x32_bf16 v[2:5], v[178:181], v[210:213], v[2:5]
	v_mfma_f32_16x16x32_bf16 v[86:89], v[174:177], v[190:193], v[86:89]
	v_mfma_f32_16x16x32_bf16 v[22:25], v[182:185], v[190:193], v[22:25]
	v_mfma_f32_16x16x32_bf16 v[82:85], v[174:177], v[198:201], v[82:85]
	v_mfma_f32_16x16x32_bf16 v[18:21], v[182:185], v[198:201], v[18:21]
	v_mfma_f32_16x16x32_bf16 v[70:73], v[174:177], v[206:209], v[70:73]
	v_mfma_f32_16x16x32_bf16 v[6:9], v[182:185], v[206:209], v[6:9]
	v_mfma_f32_16x16x32_bf16 v[66:69], v[174:177], v[214:217], v[66:69]
	v_mfma_f32_16x16x32_bf16 v[2:5], v[182:185], v[214:217], v[2:5]
	s_setprio 0
	s_barrier
	s_add_i32 s61, 0, 0x18000
	s_add_i32 s64, 0, 0x1c000
	v_add_u32_e32 v142, s61, v248
	v_add_u32_e32 v182, s64, v248
	ds_read_b128 v[130:133], v142
	ds_read_b128 v[134:137], v142 offset:1024
	ds_read_b128 v[138:141], v142 offset:2048
	ds_read_b128 v[142:145], v142 offset:3072
	ds_read_b128 v[158:161], v182
	ds_read_b128 v[174:177], v182 offset:1024
	ds_read_b128 v[178:181], v182 offset:2048
	ds_read_b128 v[182:185], v182 offset:3072
	s_add_u32 s94, vcc_lo, 0x80000
	s_addc_u32 s95, vcc_hi, 0
	s_mov_b32 m0, s87
	v_lshl_add_u64 v[226:227], s[94:95], 0, v[146:147]
	ds_read_b128 v[186:189], v251 offset:32768
	ds_read_b128 v[190:193], v251 offset:33792
	ds_read_b128 v[194:197], v251 offset:34816
	ds_read_b128 v[198:201], v251 offset:35840
	ds_read_b128 v[202:205], v251 offset:36864
	ds_read_b128 v[206:209], v251 offset:37888
	ds_read_b128 v[210:213], v251 offset:38912
	ds_read_b128 v[214:217], v251 offset:39936
	global_load_lds_dwordx4 v[226:227], off
	v_lshl_add_u64 v[226:227], s[94:95], 0, v[148:149]
	s_mov_b32 m0, s88
	s_nop 0
	global_load_lds_dwordx4 v[226:227], off
	s_waitcnt vmcnt(8)
	s_waitcnt lgkmcnt(0)
	s_barrier
	s_setprio 1
	s_waitcnt lgkmcnt(0)
	v_mfma_f32_16x16x32_bf16 v[126:129], v[130:133], v[186:189], v[126:129]
	v_mfma_f32_16x16x32_bf16 v[62:65], v[138:141], v[186:189], v[62:65]
	v_mfma_f32_16x16x32_bf16 v[118:121], v[130:133], v[194:197], v[118:121]
	v_mfma_f32_16x16x32_bf16 v[58:61], v[138:141], v[194:197], v[58:61]
	v_mfma_f32_16x16x32_bf16 v[110:113], v[130:133], v[202:205], v[110:113]
	v_mfma_f32_16x16x32_bf16 v[46:49], v[138:141], v[202:205], v[46:49]
	v_mfma_f32_16x16x32_bf16 v[106:109], v[130:133], v[210:213], v[106:109]
	v_mfma_f32_16x16x32_bf16 v[42:45], v[138:141], v[210:213], v[42:45]
	v_mfma_f32_16x16x32_bf16 v[126:129], v[134:137], v[190:193], v[126:129]
	v_mfma_f32_16x16x32_bf16 v[62:65], v[142:145], v[190:193], v[62:65]
	v_mfma_f32_16x16x32_bf16 v[118:121], v[134:137], v[198:201], v[118:121]
	v_mfma_f32_16x16x32_bf16 v[58:61], v[142:145], v[198:201], v[58:61]
	v_mfma_f32_16x16x32_bf16 v[110:113], v[134:137], v[206:209], v[110:113]
	v_mfma_f32_16x16x32_bf16 v[46:49], v[142:145], v[206:209], v[46:49]
	v_mfma_f32_16x16x32_bf16 v[106:109], v[134:137], v[214:217], v[106:109]
	v_mfma_f32_16x16x32_bf16 v[42:45], v[142:145], v[214:217], v[42:45]
	v_mfma_f32_16x16x32_bf16 v[122:125], v[158:161], v[186:189], v[122:125]
	v_mfma_f32_16x16x32_bf16 v[54:57], v[178:181], v[186:189], v[54:57]
	v_mfma_f32_16x16x32_bf16 v[114:117], v[158:161], v[194:197], v[114:117]
	v_mfma_f32_16x16x32_bf16 v[50:53], v[178:181], v[194:197], v[50:53]
	v_mfma_f32_16x16x32_bf16 v[102:105], v[158:161], v[202:205], v[102:105]
	v_mfma_f32_16x16x32_bf16 v[38:41], v[178:181], v[202:205], v[38:41]
	v_mfma_f32_16x16x32_bf16 v[98:101], v[158:161], v[210:213], v[98:101]
	v_mfma_f32_16x16x32_bf16 v[34:37], v[178:181], v[210:213], v[34:37]
	v_mfma_f32_16x16x32_bf16 v[122:125], v[174:177], v[190:193], v[122:125]
	v_mfma_f32_16x16x32_bf16 v[54:57], v[182:185], v[190:193], v[54:57]
	v_mfma_f32_16x16x32_bf16 v[114:117], v[174:177], v[198:201], v[114:117]
	v_mfma_f32_16x16x32_bf16 v[50:53], v[182:185], v[198:201], v[50:53]
	v_mfma_f32_16x16x32_bf16 v[102:105], v[174:177], v[206:209], v[102:105]
	v_mfma_f32_16x16x32_bf16 v[38:41], v[182:185], v[206:209], v[38:41]
	v_mfma_f32_16x16x32_bf16 v[98:101], v[174:177], v[214:217], v[98:101]
	v_mfma_f32_16x16x32_bf16 v[34:37], v[182:185], v[214:217], v[34:37]
	s_setprio 0
	s_barrier
; #define PG8_STAGE(bufoff, gbase, voff) do { _Pragma("unroll") for (int _i = 0; _i < 2; ++_i) \
;         __builtin_amdgcn_global_load_lds((const __attribute__((address_space(1))) unsigned*)((const char*)(gbase) + (voff)[_i]), (LAS unsigned*)(lds + (bufoff) + ldsw + _i * 8192), 16, 0, 0); } while (0)
; #define PG8_LDA(dst, b, h) do { _Pragma("unroll") for (int m = 0; m < 4; ++m) _Pragma("unroll") for (int k = 0; k < 2; ++k) dst[m][k] = *(const LAS bf16x8*)(lds + PG8_SA(b, h) + aoff + m * 2048 + k * 1024); } while (0)
; #define PG8_MMA(ai, bj, At, Bt) do { __builtin_amdgcn_s_setprio(1); _Pragma("unroll") for (int m = 0; m < 4; ++m) _Pragma("unroll") for (int n = 0; n < 2; ++n) _Pragma("unroll") for (int k = 0; k < 2; ++k) \
;         acc[ai][bj][m][n] = __builtin_amdgcn_mfma_f32_16x16x32_bf16(Bt[n][k], At[m][k], acc[ai][bj][m][n], 0, 0, 0); __builtin_amdgcn_s_setprio(0); } while (0)
; #define PG8_WAIT_V(n) asm volatile("s_waitcnt vmcnt(" #n ")" ::: "memory")
; #define PG8_WAIT_L(n) asm volatile("s_waitcnt lgkmcnt(" #n ")" ::: "memory")
; #define PG8_BAR __builtin_amdgcn_s_barrier()
; #define PG8_SCHED __builtin_amdgcn_sched_barrier(0)
; __device__ __forceinline__ float row_rstd(const float* ssp, int row, int fq) {
;     const f32x4 a = *(const f32x4*)(ssp + (size_t)row * 32 + 8 * fq), b = *(const f32x4*)(ssp + (size_t)row * 32 + 8 * fq + 4);
;     float s = ((a[0] + a[1]) + (a[2] + a[3])) + ((b[0] + b[1]) + (b[2] + b[3]));
; template <class Epi, class SchedT, bool ALIGN_EPI, bool SP2>
; __device__ __forceinline__ void gemm_phase(LAS unsigned char* lds, const int ldk, const int nt, const SchedT& S, const Epi& E) {
;     ...
;             PG8_LDA(At, 1, 1); PG8_STAGE(PG8_SB(1, 0), b3, voffB); PG8_STAGE(PG8_SB(1, 1), b3 + hstepB, voffB); PG8_STAGE(PG8_SA(1, 0), a3, voffA);
;             PG8_WAIT_V(8); PG8_WAIT_L(0); PG8_BAR; PG8_MMA(1, 0, At, B0); PG8_MMA(1, 1, At, B1); PG8_BAR; PG8_SCHED;
	s_add_i32 s61, s61, s84
	v_lshl_add_u64 v[218:219], v[218:219], 0, s[24:25]
	s_mov_b32 m0, s61
	ds_read_b128 v[186:189], v251 offset:49152
	ds_read_b128 v[190:193], v251 offset:50176
	ds_read_b128 v[194:197], v251 offset:51200
	ds_read_b128 v[198:201], v251 offset:52224
	ds_read_b128 v[202:205], v251 offset:53248
	ds_read_b128 v[206:209], v251 offset:54272
	ds_read_b128 v[210:213], v251 offset:55296
	ds_read_b128 v[214:217], v251 offset:56320
	global_load_lds_dwordx4 v[218:219], off
	s_add_i32 m0, s61, 0x2000
	s_add_u32 s36, s36, 0x20080
	v_lshl_add_u64 v[218:219], v[220:221], 0, s[24:25]
	s_addc_u32 s37, s37, 0
	s_add_i32 s61, s64, s84
	global_load_lds_dwordx4 v[218:219], off
	v_lshl_add_u64 v[218:219], s[36:37], 0, v[0:1]
	s_mov_b32 m0, s61
	s_nop 0
	global_load_lds_dwordx4 v[218:219], off
	v_lshl_add_u64 v[218:219], s[36:37], 0, v[150:151]
	s_add_i32 m0, s61, 0x2000
	s_nop 0
	global_load_lds_dwordx4 v[218:219], off
	v_lshl_add_u64 v[218:219], v[222:223], 0, s[24:25]
	s_mov_b32 m0, s89
	s_nop 0
	global_load_lds_dwordx4 v[218:219], off
	v_lshl_add_u64 v[218:219], v[224:225], 0, s[24:25]
	s_mov_b32 m0, s90
	s_nop 0
	global_load_lds_dwordx4 v[218:219], off
	s_waitcnt vmcnt(8)
	s_waitcnt lgkmcnt(0)
	s_barrier
	s_setprio 1
	s_waitcnt lgkmcnt(0)
	v_mfma_f32_16x16x32_bf16 v[94:97], v[130:133], v[186:189], v[94:97]
	v_mfma_f32_16x16x32_bf16 v[30:33], v[138:141], v[186:189], v[30:33]
	v_mfma_f32_16x16x32_bf16 v[90:93], v[130:133], v[194:197], v[90:93]
	v_mfma_f32_16x16x32_bf16 v[26:29], v[138:141], v[194:197], v[26:29]
	v_mfma_f32_16x16x32_bf16 v[78:81], v[130:133], v[202:205], v[78:81]
	v_mfma_f32_16x16x32_bf16 v[14:17], v[138:141], v[202:205], v[14:17]
	v_mfma_f32_16x16x32_bf16 v[74:77], v[130:133], v[210:213], v[74:77]
	v_mfma_f32_16x16x32_bf16 v[10:13], v[138:141], v[210:213], v[10:13]
	v_mfma_f32_16x16x32_bf16 v[94:97], v[134:137], v[190:193], v[94:97]
	v_mfma_f32_16x16x32_bf16 v[30:33], v[142:145], v[190:193], v[30:33]
	v_mfma_f32_16x16x32_bf16 v[90:93], v[134:137], v[198:201], v[90:93]
	v_mfma_f32_16x16x32_bf16 v[26:29], v[142:145], v[198:201], v[26:29]
	v_mfma_f32_16x16x32_bf16 v[78:81], v[134:137], v[206:209], v[78:81]
	v_mfma_f32_16x16x32_bf16 v[14:17], v[142:145], v[206:209], v[14:17]
	v_mfma_f32_16x16x32_bf16 v[74:77], v[134:137], v[214:217], v[74:77]
	v_mfma_f32_16x16x32_bf16 v[10:13], v[142:145], v[214:217], v[10:13]
	v_mfma_f32_16x16x32_bf16 v[86:89], v[158:161], v[186:189], v[86:89]
	v_mfma_f32_16x16x32_bf16 v[22:25], v[178:181], v[186:189], v[22:25]
	v_mfma_f32_16x16x32_bf16 v[82:85], v[158:161], v[194:197], v[82:85]
	v_mfma_f32_16x16x32_bf16 v[18:21], v[178:181], v[194:197], v[18:21]
	v_mfma_f32_16x16x32_bf16 v[70:73], v[158:161], v[202:205], v[70:73]
	v_mfma_f32_16x16x32_bf16 v[6:9], v[178:181], v[202:205], v[6:9]
	v_mfma_f32_16x16x32_bf16 v[66:69], v[158:161], v[210:213], v[66:69]
	v_mfma_f32_16x16x32_bf16 v[2:5], v[178:181], v[210:213], v[2:5]
	v_mfma_f32_16x16x32_bf16 v[86:89], v[174:177], v[190:193], v[86:89]
	v_mfma_f32_16x16x32_bf16 v[22:25], v[182:185], v[190:193], v[22:25]
	v_mfma_f32_16x16x32_bf16 v[82:85], v[174:177], v[198:201], v[82:85]
	v_mfma_f32_16x16x32_bf16 v[18:21], v[182:185], v[198:201], v[18:21]
	v_mfma_f32_16x16x32_bf16 v[70:73], v[174:177], v[206:209], v[70:73]
	v_mfma_f32_16x16x32_bf16 v[6:9], v[182:185], v[206:209], v[6:9]
	v_mfma_f32_16x16x32_bf16 v[66:69], v[174:177], v[214:217], v[66:69]
	v_mfma_f32_16x16x32_bf16 v[2:5], v[182:185], v[214:217], v[2:5]
	s_setprio 0
	s_barrier
	s_add_i32 s59, s59, 2
	s_add_u32 s34, s34, 0x100
	s_addc_u32 s35, s35, 0
	s_add_u32 s13, s13, 0x100
	s_addc_u32 s17, s17, 0
	s_cmp_gt_u32 s59, 29
	s_cbranch_scc0 .LBB0_752
	v_lshl_add_u32 v130, s12, 8, v247
	v_lshlrev_b32_e32 v140, 7, v130
	v_mov_b32_e32 v141, 0
	v_lshl_add_u64 v[132:133], v[152:153], 0, v[140:141]
	v_add_u32_e32 v140, 0x1000, v140
	v_lshl_add_u64 v[134:135], v[152:153], 0, v[140:141]
	v_add_u32_e32 v140, 0x3000, v140
	v_lshl_add_u64 v[136:137], v[152:153], 0, v[140:141]
	v_add_u32_e32 v140, 0x1000, v140
	v_lshl_add_u64 v[138:139], v[152:153], 0, v[140:141]
	global_load_dwordx4 v[174:177], v[132:133], off
	global_load_dwordx4 v[178:181], v[132:133], off offset:16
	global_load_dwordx4 v[182:185], v[132:133], off offset:2048
	global_load_dwordx4 v[186:189], v[132:133], off offset:2064
	global_load_dwordx4 v[190:193], v[134:135], off
	global_load_dwordx4 v[194:197], v[134:135], off offset:16
	global_load_dwordx4 v[198:201], v[134:135], off offset:2048
	global_load_dwordx4 v[202:205], v[134:135], off offset:2064
	global_load_dwordx4 v[206:209], v[136:137], off
	global_load_dwordx4 v[210:213], v[136:137], off offset:16
	global_load_dwordx4 v[214:217], v[136:137], off offset:2048
	global_load_dwordx4 v[218:221], v[136:137], off offset:2064
	global_load_dwordx4 v[222:225], v[138:139], off
	global_load_dwordx4 v[226:229], v[138:139], off offset:16
	global_load_dwordx4 v[230:233], v[138:139], off offset:2048
	global_load_dwordx4 v[234:237], v[138:139], off offset:2064
	v_xor_b32_e32 v238, 16, v241
	v_xor_b32_e32 v239, 32, v241
	v_lshlrev_b32_e32 v238, 2, v238
	v_lshlrev_b32_e32 v239, 2, v239
	s_and_b64 vcc, exec, s[56:57]
	s_cbranch_vccz .LBB0_755
	s_barrier

; #define PG8_STAGE(bufoff, gbase, voff) do { _Pragma("unroll") for (int _i = 0; _i < 2; ++_i) \
;         __builtin_amdgcn_global_load_lds((const __attribute__((address_space(1))) unsigned*)((const char*)(gbase) + (voff)[_i]), (LAS unsigned*)(lds + (bufoff) + ldsw + _i * 8192), 16, 0, 0); } while (0)
; #define PG8_LDA(dst, b, h) do { _Pragma("unroll") for (int m = 0; m < 4; ++m) _Pragma("unroll") for (int k = 0; k < 2; ++k) dst[m][k] = *(const LAS bf16x8*)(lds + PG8_SA(b, h) + aoff + m * 2048 + k * 1024); } while (0)
; #define PG8_LDB(dst, b, h) do { _Pragma("unroll") for (int n = 0; n < 2; ++n) _Pragma("unroll") for (int k = 0; k < 2; ++k) dst[n][k] = *(const LAS bf16x8*)(lds + PG8_SB(b, h) + boff + n * 2048 + k * 1024); } while (0)
; #define PG8_MMA(ai, bj, At, Bt) do { __builtin_amdgcn_s_setprio(1); _Pragma("unroll") for (int m = 0; m < 4; ++m) _Pragma("unroll") for (int n = 0; n < 2; ++n) _Pragma("unroll") for (int k = 0; k < 2; ++k) \
;         acc[ai][bj][m][n] = __builtin_amdgcn_mfma_f32_16x16x32_bf16(Bt[n][k], At[m][k], acc[ai][bj][m][n], 0, 0, 0); __builtin_amdgcn_s_setprio(0); } while (0)
; #define PG8_WAIT_V(n) asm volatile("s_waitcnt vmcnt(" #n ")" ::: "memory")
; #define PG8_WAIT_L(n) asm volatile("s_waitcnt lgkmcnt(" #n ")" ::: "memory")
; #define PG8_BAR __builtin_amdgcn_s_barrier()
; #define PG8_SCHED __builtin_amdgcn_sched_barrier(0)
; template <class Epi, class SchedT, bool ALIGN_EPI, bool SP2>
; __device__ __forceinline__ void gemm_phase(LAS unsigned char* lds, const int ldk, const int nt, const SchedT& S, const Epi& E) {
;     ...
;             PG8_LDB(B0, 0, 0); PG8_LDB(B1, 0, 1); PG8_SCHED; PG8_LDA(At, 0, 0); PG8_STAGE(PG8_SA(1, 1), a1 + hstep, voffA);
;             PG8_WAIT_V(8); PG8_WAIT_L(0); PG8_BAR; PG8_MMA(0, 0, At, B0); PG8_MMA(0, 1, At, B1); PG8_BAR; PG8_SCHED;
;             PG8_LDA(At, 0, 1); PG8_STAGE(PG8_SB(0, 0), b2, voffB); PG8_STAGE(PG8_SB(0, 1), b2 + hstepB, voffB); PG8_STAGE(PG8_SA(0, 0), a2, voffA);
;             PG8_WAIT_V(8); PG8_WAIT_L(0); PG8_BAR; PG8_MMA(1, 0, At, B0); PG8_MMA(1, 1, At, B1); PG8_BAR; PG8_SCHED;
.LBB0_948:
	s_add_u32 s16, s12, 0x100
	s_addc_u32 s17, s13, 0
	s_add_i32 s64, 0, 0x10000
	s_cmpk_eq_i32 s83, 0x52
	s_cselect_b32 s47, s1, s17
	s_cselect_b32 s46, s0, s16
	v_add_u32_e32 v144, s64, v147
	s_cselect_b32 s45, s43, s82
	s_cselect_b32 s44, s42, s81
	s_add_i32 s65, 0, 0x14000
	ds_read_b128 v[140:143], v144
	ds_read_b128 v[150:153], v144 offset:1024
	ds_read_b128 v[154:157], v144 offset:2048
	ds_read_b128 v[158:161], v144 offset:3072
	v_add_u32_e32 v144, s65, v147
	ds_read_b128 v[174:177], v144
	ds_read_b128 v[178:181], v144 offset:1024
	ds_read_b128 v[182:185], v144 offset:2048
	ds_read_b128 v[186:189], v144 offset:3072
	v_lshl_add_u64 v[144:145], s[12:13], 0, v[136:137]
	s_add_i32 m0, s53, 0xc000
	ds_read_b128 v[190:193], v149
	ds_read_b128 v[194:197], v149 offset:1024
	ds_read_b128 v[198:201], v149 offset:2048
	ds_read_b128 v[202:205], v149 offset:3072
	ds_read_b128 v[206:209], v149 offset:4096
	ds_read_b128 v[210:213], v149 offset:5120
	ds_read_b128 v[214:217], v149 offset:6144
	ds_read_b128 v[218:221], v149 offset:7168
	global_load_lds_dwordx4 v[144:145], off
	v_lshl_add_u64 v[144:145], s[12:13], 0, v[138:139]
	s_add_i32 m0, s53, 0xe000
	s_nop 0
	global_load_lds_dwordx4 v[144:145], off
	s_waitcnt vmcnt(8)
	s_waitcnt lgkmcnt(0)
	s_barrier
	s_setprio 1
	s_waitcnt lgkmcnt(0)
	v_mfma_f32_16x16x32_bf16 v[126:129], v[140:143], v[190:193], v[126:129]
	v_mfma_f32_16x16x32_bf16 v[122:125], v[154:157], v[190:193], v[122:125]
	v_mfma_f32_16x16x32_bf16 v[110:113], v[140:143], v[198:201], v[110:113]
	v_mfma_f32_16x16x32_bf16 v[106:109], v[154:157], v[198:201], v[106:109]
	v_mfma_f32_16x16x32_bf16 v[94:97], v[140:143], v[206:209], v[94:97]
	v_mfma_f32_16x16x32_bf16 v[90:93], v[154:157], v[206:209], v[90:93]
	v_mfma_f32_16x16x32_bf16 v[78:81], v[140:143], v[214:217], v[78:81]
	v_mfma_f32_16x16x32_bf16 v[74:77], v[154:157], v[214:217], v[74:77]
	v_mfma_f32_16x16x32_bf16 v[126:129], v[150:153], v[194:197], v[126:129]
	v_mfma_f32_16x16x32_bf16 v[122:125], v[158:161], v[194:197], v[122:125]
	v_mfma_f32_16x16x32_bf16 v[110:113], v[150:153], v[202:205], v[110:113]
	v_mfma_f32_16x16x32_bf16 v[106:109], v[158:161], v[202:205], v[106:109]
	v_mfma_f32_16x16x32_bf16 v[94:97], v[150:153], v[210:213], v[94:97]
	v_mfma_f32_16x16x32_bf16 v[90:93], v[158:161], v[210:213], v[90:93]
	v_mfma_f32_16x16x32_bf16 v[78:81], v[150:153], v[218:221], v[78:81]
	v_mfma_f32_16x16x32_bf16 v[74:77], v[158:161], v[218:221], v[74:77]
	v_mfma_f32_16x16x32_bf16 v[118:121], v[174:177], v[190:193], v[118:121]
	v_mfma_f32_16x16x32_bf16 v[114:117], v[182:185], v[190:193], v[114:117]
	v_mfma_f32_16x16x32_bf16 v[102:105], v[174:177], v[198:201], v[102:105]
	v_mfma_f32_16x16x32_bf16 v[98:101], v[182:185], v[198:201], v[98:101]
	v_mfma_f32_16x16x32_bf16 v[86:89], v[174:177], v[206:209], v[86:89]
	v_mfma_f32_16x16x32_bf16 v[82:85], v[182:185], v[206:209], v[82:85]
	v_mfma_f32_16x16x32_bf16 v[70:73], v[174:177], v[214:217], v[70:73]
	v_mfma_f32_16x16x32_bf16 v[66:69], v[182:185], v[214:217], v[66:69]
	v_mfma_f32_16x16x32_bf16 v[118:121], v[178:181], v[194:197], v[118:121]
	v_mfma_f32_16x16x32_bf16 v[114:117], v[186:189], v[194:197], v[114:117]
	v_mfma_f32_16x16x32_bf16 v[102:105], v[178:181], v[202:205], v[102:105]
	v_mfma_f32_16x16x32_bf16 v[98:101], v[186:189], v[202:205], v[98:101]
	v_mfma_f32_16x16x32_bf16 v[86:89], v[178:181], v[210:213], v[86:89]
	v_mfma_f32_16x16x32_bf16 v[82:85], v[186:189], v[210:213], v[82:85]
	v_mfma_f32_16x16x32_bf16 v[70:73], v[178:181], v[218:221], v[70:73]
	v_mfma_f32_16x16x32_bf16 v[66:69], v[186:189], v[218:221], v[66:69]
	s_setprio 0
	s_barrier
	s_add_i32 s12, s64, s52
	v_lshl_add_u64 v[144:145], s[44:45], 0, v[0:1]
	s_mov_b32 m0, s12
	ds_read_b128 v[190:193], v149 offset:16384
	ds_read_b128 v[194:197], v149 offset:17408
	ds_read_b128 v[198:201], v149 offset:18432
	ds_read_b128 v[202:205], v149 offset:19456
	ds_read_b128 v[206:209], v149 offset:20480
	ds_read_b128 v[210:213], v149 offset:21504
	ds_read_b128 v[214:217], v149 offset:22528
	ds_read_b128 v[218:221], v149 offset:23552
	global_load_lds_dwordx4 v[144:145], off
	s_add_i32 m0, s12, 0x2000
	s_add_u32 s12, s44, 0x56000
	v_lshl_add_u64 v[222:223], s[44:45], 0, v[134:135]
	s_addc_u32 s13, s45, 0
	s_add_i32 s64, s65, s52
	global_load_lds_dwordx4 v[222:223], off
	v_lshl_add_u64 v[224:225], s[12:13], 0, v[0:1]
	s_mov_b32 m0, s64
	v_lshl_add_u64 v[226:227], s[46:47], 0, v[132:133]
	global_load_lds_dwordx4 v[224:225], off
	v_lshl_add_u64 v[224:225], s[12:13], 0, v[134:135]
	s_add_i32 m0, s64, 0x2000
	s_nop 0
	global_load_lds_dwordx4 v[224:225], off
	v_lshl_add_u64 v[224:225], s[46:47], 0, v[130:131]
	s_mov_b32 m0, s53
	s_nop 0
	global_load_lds_dwordx4 v[224:225], off
	s_mov_b32 m0, s54
	s_nop 0
	global_load_lds_dwordx4 v[226:227], off
	s_waitcnt vmcnt(8)
	s_waitcnt lgkmcnt(0)
	s_barrier
; #define PG8_STAGE(bufoff, gbase, voff) do { _Pragma("unroll") for (int _i = 0; _i < 2; ++_i) \
;         __builtin_amdgcn_global_load_lds((const __attribute__((address_space(1))) unsigned*)((const char*)(gbase) + (voff)[_i]), (LAS unsigned*)(lds + (bufoff) + ldsw + _i * 8192), 16, 0, 0); } while (0)
; #define PG8_LDA(dst, b, h) do { _Pragma("unroll") for (int m = 0; m < 4; ++m) _Pragma("unroll") for (int k = 0; k < 2; ++k) dst[m][k] = *(const LAS bf16x8*)(lds + PG8_SA(b, h) + aoff + m * 2048 + k * 1024); } while (0)
; #define PG8_LDB(dst, b, h) do { _Pragma("unroll") for (int n = 0; n < 2; ++n) _Pragma("unroll") for (int k = 0; k < 2; ++k) dst[n][k] = *(const LAS bf16x8*)(lds + PG8_SB(b, h) + boff + n * 2048 + k * 1024); } while (0)
; #define PG8_MMA(ai, bj, At, Bt) do { __builtin_amdgcn_s_setprio(1); _Pragma("unroll") for (int m = 0; m < 4; ++m) _Pragma("unroll") for (int n = 0; n < 2; ++n) _Pragma("unroll") for (int k = 0; k < 2; ++k) \
;         acc[ai][bj][m][n] = __builtin_amdgcn_mfma_f32_16x16x32_bf16(Bt[n][k], At[m][k], acc[ai][bj][m][n], 0, 0, 0); __builtin_amdgcn_s_setprio(0); } while (0)
; #define PG8_WAIT_V(n) asm volatile("s_waitcnt vmcnt(" #n ")" ::: "memory")
; #define PG8_WAIT_L(n) asm volatile("s_waitcnt lgkmcnt(" #n ")" ::: "memory")
; #define PG8_BAR __builtin_amdgcn_s_barrier()
; #define PG8_SCHED __builtin_amdgcn_sched_barrier(0)
; template <class Epi, class SchedT, bool ALIGN_EPI, bool SP2>
; __device__ __forceinline__ void gemm_phase(LAS unsigned char* lds, const int ldk, const int nt, const SchedT& S, const Epi& E) {
;     ...
;             PG8_WAIT_V(8); PG8_WAIT_L(0); PG8_BAR; PG8_MMA(1, 0, At, B0); PG8_MMA(1, 1, At, B1); PG8_BAR; PG8_SCHED;
;             PG8_LDB(B0, 1, 0); PG8_LDB(B1, 1, 1); PG8_SCHED; PG8_LDA(At, 1, 0); PG8_STAGE(PG8_SA(0, 1), a2 + hstep, voffA);
;             PG8_WAIT_V(8); PG8_WAIT_L(0); PG8_BAR; PG8_MMA(0, 0, At, B0); PG8_MMA(0, 1, At, B1); PG8_BAR; PG8_SCHED;
	s_setprio 1
	s_waitcnt lgkmcnt(0)
	v_mfma_f32_16x16x32_bf16 v[62:65], v[140:143], v[190:193], v[62:65]
	v_mfma_f32_16x16x32_bf16 v[58:61], v[154:157], v[190:193], v[58:61]
	v_mfma_f32_16x16x32_bf16 v[46:49], v[140:143], v[198:201], v[46:49]
	v_mfma_f32_16x16x32_bf16 v[42:45], v[154:157], v[198:201], v[42:45]
	v_mfma_f32_16x16x32_bf16 v[30:33], v[140:143], v[206:209], v[30:33]
	v_mfma_f32_16x16x32_bf16 v[26:29], v[154:157], v[206:209], v[26:29]
	v_mfma_f32_16x16x32_bf16 v[14:17], v[140:143], v[214:217], v[14:17]
	v_mfma_f32_16x16x32_bf16 v[10:13], v[154:157], v[214:217], v[10:13]
	v_mfma_f32_16x16x32_bf16 v[62:65], v[150:153], v[194:197], v[62:65]
	v_mfma_f32_16x16x32_bf16 v[58:61], v[158:161], v[194:197], v[58:61]
	v_mfma_f32_16x16x32_bf16 v[46:49], v[150:153], v[202:205], v[46:49]
	v_mfma_f32_16x16x32_bf16 v[42:45], v[158:161], v[202:205], v[42:45]
	v_mfma_f32_16x16x32_bf16 v[30:33], v[150:153], v[210:213], v[30:33]
	v_mfma_f32_16x16x32_bf16 v[26:29], v[158:161], v[210:213], v[26:29]
	v_mfma_f32_16x16x32_bf16 v[14:17], v[150:153], v[218:221], v[14:17]
	v_mfma_f32_16x16x32_bf16 v[10:13], v[158:161], v[218:221], v[10:13]
	v_mfma_f32_16x16x32_bf16 v[54:57], v[174:177], v[190:193], v[54:57]
	v_mfma_f32_16x16x32_bf16 v[50:53], v[182:185], v[190:193], v[50:53]
	v_mfma_f32_16x16x32_bf16 v[38:41], v[174:177], v[198:201], v[38:41]
	v_mfma_f32_16x16x32_bf16 v[34:37], v[182:185], v[198:201], v[34:37]
	v_mfma_f32_16x16x32_bf16 v[22:25], v[174:177], v[206:209], v[22:25]
	v_mfma_f32_16x16x32_bf16 v[18:21], v[182:185], v[206:209], v[18:21]
	v_mfma_f32_16x16x32_bf16 v[6:9], v[174:177], v[214:217], v[6:9]
	v_mfma_f32_16x16x32_bf16 v[2:5], v[182:185], v[214:217], v[2:5]
	v_mfma_f32_16x16x32_bf16 v[54:57], v[178:181], v[194:197], v[54:57]
	v_mfma_f32_16x16x32_bf16 v[50:53], v[186:189], v[194:197], v[50:53]
	v_mfma_f32_16x16x32_bf16 v[38:41], v[178:181], v[202:205], v[38:41]
	v_mfma_f32_16x16x32_bf16 v[34:37], v[186:189], v[202:205], v[34:37]
	v_mfma_f32_16x16x32_bf16 v[22:25], v[178:181], v[210:213], v[22:25]
	v_mfma_f32_16x16x32_bf16 v[18:21], v[186:189], v[210:213], v[18:21]
	v_mfma_f32_16x16x32_bf16 v[6:9], v[178:181], v[218:221], v[6:9]
	v_mfma_f32_16x16x32_bf16 v[2:5], v[186:189], v[218:221], v[2:5]
	s_setprio 0
	s_barrier
	s_add_i32 s64, 0, 0x18000
	s_add_i32 s65, 0, 0x1c000
	v_add_u32_e32 v158, s64, v147
	v_add_u32_e32 v186, s65, v147
	ds_read_b128 v[140:143], v158
	ds_read_b128 v[150:153], v158 offset:1024
	ds_read_b128 v[154:157], v158 offset:2048
	ds_read_b128 v[158:161], v158 offset:3072
	ds_read_b128 v[174:177], v186
	ds_read_b128 v[178:181], v186 offset:1024
	ds_read_b128 v[182:185], v186 offset:2048
	ds_read_b128 v[186:189], v186 offset:3072
	s_add_u32 s12, s46, 0x158000
	s_addc_u32 s13, s47, 0
	s_mov_b32 m0, s55
	v_lshl_add_u64 v[228:229], s[12:13], 0, v[130:131]
	ds_read_b128 v[190:193], v149 offset:32768
	ds_read_b128 v[194:197], v149 offset:33792
	ds_read_b128 v[198:201], v149 offset:34816
	ds_read_b128 v[202:205], v149 offset:35840
	ds_read_b128 v[206:209], v149 offset:36864
	ds_read_b128 v[210:213], v149 offset:37888
	ds_read_b128 v[214:217], v149 offset:38912
	ds_read_b128 v[218:221], v149 offset:39936
	global_load_lds_dwordx4 v[228:229], off
	v_lshl_add_u64 v[228:229], s[12:13], 0, v[132:133]
	s_mov_b32 m0, s56
	s_nop 0
	global_load_lds_dwordx4 v[228:229], off
	s_waitcnt vmcnt(8)
	s_waitcnt lgkmcnt(0)
	s_barrier
	s_setprio 1
	s_waitcnt lgkmcnt(0)
	v_mfma_f32_16x16x32_bf16 v[126:129], v[140:143], v[190:193], v[126:129]
	v_mfma_f32_16x16x32_bf16 v[122:125], v[154:157], v[190:193], v[122:125]
	v_mfma_f32_16x16x32_bf16 v[110:113], v[140:143], v[198:201], v[110:113]
	v_mfma_f32_16x16x32_bf16 v[106:109], v[154:157], v[198:201], v[106:109]
	v_mfma_f32_16x16x32_bf16 v[94:97], v[140:143], v[206:209], v[94:97]
	v_mfma_f32_16x16x32_bf16 v[90:93], v[154:157], v[206:209], v[90:93]
	v_mfma_f32_16x16x32_bf16 v[78:81], v[140:143], v[214:217], v[78:81]
	v_mfma_f32_16x16x32_bf16 v[74:77], v[154:157], v[214:217], v[74:77]
	v_mfma_f32_16x16x32_bf16 v[126:129], v[150:153], v[194:197], v[126:129]
	v_mfma_f32_16x16x32_bf16 v[122:125], v[158:161], v[194:197], v[122:125]
	v_mfma_f32_16x16x32_bf16 v[110:113], v[150:153], v[202:205], v[110:113]
	v_mfma_f32_16x16x32_bf16 v[106:109], v[158:161], v[202:205], v[106:109]
	v_mfma_f32_16x16x32_bf16 v[94:97], v[150:153], v[210:213], v[94:97]
	v_mfma_f32_16x16x32_bf16 v[90:93], v[158:161], v[210:213], v[90:93]
	v_mfma_f32_16x16x32_bf16 v[78:81], v[150:153], v[218:221], v[78:81]
	v_mfma_f32_16x16x32_bf16 v[74:77], v[158:161], v[218:221], v[74:77]
	v_mfma_f32_16x16x32_bf16 v[118:121], v[174:177], v[190:193], v[118:121]
	v_mfma_f32_16x16x32_bf16 v[114:117], v[182:185], v[190:193], v[114:117]
	v_mfma_f32_16x16x32_bf16 v[102:105], v[174:177], v[198:201], v[102:105]
	v_mfma_f32_16x16x32_bf16 v[98:101], v[182:185], v[198:201], v[98:101]
	v_mfma_f32_16x16x32_bf16 v[86:89], v[174:177], v[206:209], v[86:89]
	v_mfma_f32_16x16x32_bf16 v[82:85], v[182:185], v[206:209], v[82:85]
	v_mfma_f32_16x16x32_bf16 v[70:73], v[174:177], v[214:217], v[70:73]
	v_mfma_f32_16x16x32_bf16 v[66:69], v[182:185], v[214:217], v[66:69]
	v_mfma_f32_16x16x32_bf16 v[118:121], v[178:181], v[194:197], v[118:121]
	v_mfma_f32_16x16x32_bf16 v[114:117], v[186:189], v[194:197], v[114:117]
	v_mfma_f32_16x16x32_bf16 v[102:105], v[178:181], v[202:205], v[102:105]
	v_mfma_f32_16x16x32_bf16 v[98:101], v[186:189], v[202:205], v[98:101]
	v_mfma_f32_16x16x32_bf16 v[86:89], v[178:181], v[210:213], v[86:89]
	v_mfma_f32_16x16x32_bf16 v[82:85], v[186:189], v[210:213], v[82:85]
	v_mfma_f32_16x16x32_bf16 v[70:73], v[178:181], v[218:221], v[70:73]
	v_mfma_f32_16x16x32_bf16 v[66:69], v[186:189], v[218:221], v[66:69]
	s_setprio 0
	s_barrier
; #define PG8_STAGE(bufoff, gbase, voff) do { _Pragma("unroll") for (int _i = 0; _i < 2; ++_i) \
;         __builtin_amdgcn_global_load_lds((const __attribute__((address_space(1))) unsigned*)((const char*)(gbase) + (voff)[_i]), (LAS unsigned*)(lds + (bufoff) + ldsw + _i * 8192), 16, 0, 0); } while (0)
; #define PG8_LDA(dst, b, h) do { _Pragma("unroll") for (int m = 0; m < 4; ++m) _Pragma("unroll") for (int k = 0; k < 2; ++k) dst[m][k] = *(const LAS bf16x8*)(lds + PG8_SA(b, h) + aoff + m * 2048 + k * 1024); } while (0)
; #define PG8_MMA(ai, bj, At, Bt) do { __builtin_amdgcn_s_setprio(1); _Pragma("unroll") for (int m = 0; m < 4; ++m) _Pragma("unroll") for (int n = 0; n < 2; ++n) _Pragma("unroll") for (int k = 0; k < 2; ++k) \
;         acc[ai][bj][m][n] = __builtin_amdgcn_mfma_f32_16x16x32_bf16(Bt[n][k], At[m][k], acc[ai][bj][m][n], 0, 0, 0); __builtin_amdgcn_s_setprio(0); } while (0)
; #define PG8_WAIT_V(n) asm volatile("s_waitcnt vmcnt(" #n ")" ::: "memory")
; #define PG8_WAIT_L(n) asm volatile("s_waitcnt lgkmcnt(" #n ")" ::: "memory")
; #define PG8_BAR __builtin_amdgcn_s_barrier()
; #define PG8_SCHED __builtin_amdgcn_sched_barrier(0)
; template <class Epi, class SchedT, bool ALIGN_EPI, bool SP2>
; __device__ __forceinline__ void gemm_phase(LAS unsigned char* lds, const int ldk, const int nt, const SchedT& S, const Epi& E) {
;     ...
;             PG8_LDA(At, 1, 1); PG8_STAGE(PG8_SB(1, 0), b3, voffB); PG8_STAGE(PG8_SB(1, 1), b3 + hstepB, voffB); PG8_STAGE(PG8_SA(1, 0), a3, voffA);
;             PG8_WAIT_V(8); PG8_WAIT_L(0); PG8_BAR; PG8_MMA(1, 0, At, B0); PG8_MMA(1, 1, At, B1); PG8_BAR; PG8_SCHED;
;     __device__ __forceinline__ void operator()(f32x4 (&acc)[2][2][4][2], const Unit& u, int wr, int wc, int fr, int fq) const {
;     ...
;                 const int row = row0 + ai * HALF + m * 16; float sq = 0.f;
; #pragma unroll
;                 for (int bj = 0; bj < 2; ++bj) {
;                     const size_t off = (size_t)row * D + col0 + bj * 32;
;                     const u32x4 xw = *(const u32x4*)(xin + off);
	s_add_i32 s12, s64, s52
	v_lshl_add_u64 v[144:145], v[144:145], 0, s[24:25]
	s_mov_b32 m0, s12
	ds_read_b128 v[190:193], v149 offset:49152
	ds_read_b128 v[194:197], v149 offset:50176
	ds_read_b128 v[198:201], v149 offset:51200
	ds_read_b128 v[202:205], v149 offset:52224
	ds_read_b128 v[206:209], v149 offset:53248
	ds_read_b128 v[210:213], v149 offset:54272
	ds_read_b128 v[214:217], v149 offset:55296
	ds_read_b128 v[218:221], v149 offset:56320
	global_load_lds_dwordx4 v[144:145], off
	s_add_i32 m0, s12, 0x2000
	s_add_u32 s12, s44, 0x56080
	v_lshl_add_u64 v[144:145], v[222:223], 0, s[24:25]
	s_addc_u32 s13, s45, 0
	s_add_i32 s44, s65, s52
	global_load_lds_dwordx4 v[144:145], off
	v_lshl_add_u64 v[144:145], s[12:13], 0, v[0:1]
	s_mov_b32 m0, s44
	s_nop 0
	global_load_lds_dwordx4 v[144:145], off
	v_lshl_add_u64 v[144:145], s[12:13], 0, v[134:135]
	s_add_i32 m0, s44, 0x2000
	s_nop 0
	global_load_lds_dwordx4 v[144:145], off
	v_lshl_add_u64 v[144:145], v[224:225], 0, s[24:25]
	s_mov_b32 m0, s58
	s_nop 0
	global_load_lds_dwordx4 v[144:145], off
	v_lshl_add_u64 v[144:145], v[226:227], 0, s[24:25]
	s_mov_b32 m0, s59
	s_nop 0
	global_load_lds_dwordx4 v[144:145], off
	s_waitcnt vmcnt(8)
	s_waitcnt lgkmcnt(0)
	s_barrier
	s_setprio 1
	s_waitcnt lgkmcnt(0)
	v_mfma_f32_16x16x32_bf16 v[62:65], v[140:143], v[190:193], v[62:65]
	v_mfma_f32_16x16x32_bf16 v[58:61], v[154:157], v[190:193], v[58:61]
	v_mfma_f32_16x16x32_bf16 v[46:49], v[140:143], v[198:201], v[46:49]
	v_mfma_f32_16x16x32_bf16 v[42:45], v[154:157], v[198:201], v[42:45]
	v_mfma_f32_16x16x32_bf16 v[30:33], v[140:143], v[206:209], v[30:33]
	v_mfma_f32_16x16x32_bf16 v[26:29], v[154:157], v[206:209], v[26:29]
	v_mfma_f32_16x16x32_bf16 v[14:17], v[140:143], v[214:217], v[14:17]
	v_mfma_f32_16x16x32_bf16 v[10:13], v[154:157], v[214:217], v[10:13]
	v_mfma_f32_16x16x32_bf16 v[62:65], v[150:153], v[194:197], v[62:65]
	v_mfma_f32_16x16x32_bf16 v[58:61], v[158:161], v[194:197], v[58:61]
	v_mfma_f32_16x16x32_bf16 v[46:49], v[150:153], v[202:205], v[46:49]
	v_mfma_f32_16x16x32_bf16 v[42:45], v[158:161], v[202:205], v[42:45]
	v_mfma_f32_16x16x32_bf16 v[30:33], v[150:153], v[210:213], v[30:33]
	v_mfma_f32_16x16x32_bf16 v[26:29], v[158:161], v[210:213], v[26:29]
	v_mfma_f32_16x16x32_bf16 v[14:17], v[150:153], v[218:221], v[14:17]
	v_mfma_f32_16x16x32_bf16 v[10:13], v[158:161], v[218:221], v[10:13]
	v_mfma_f32_16x16x32_bf16 v[54:57], v[174:177], v[190:193], v[54:57]
	v_mfma_f32_16x16x32_bf16 v[50:53], v[182:185], v[190:193], v[50:53]
	v_mfma_f32_16x16x32_bf16 v[38:41], v[174:177], v[198:201], v[38:41]
	v_mfma_f32_16x16x32_bf16 v[34:37], v[182:185], v[198:201], v[34:37]
	v_mfma_f32_16x16x32_bf16 v[22:25], v[174:177], v[206:209], v[22:25]
	v_mfma_f32_16x16x32_bf16 v[18:21], v[182:185], v[206:209], v[18:21]
	v_mfma_f32_16x16x32_bf16 v[6:9], v[174:177], v[214:217], v[6:9]
	v_mfma_f32_16x16x32_bf16 v[2:5], v[182:185], v[214:217], v[2:5]
	v_mfma_f32_16x16x32_bf16 v[54:57], v[178:181], v[194:197], v[54:57]
	v_mfma_f32_16x16x32_bf16 v[50:53], v[186:189], v[194:197], v[50:53]
	v_mfma_f32_16x16x32_bf16 v[38:41], v[178:181], v[202:205], v[38:41]
	v_mfma_f32_16x16x32_bf16 v[34:37], v[186:189], v[202:205], v[34:37]
	v_mfma_f32_16x16x32_bf16 v[22:25], v[178:181], v[210:213], v[22:25]
	v_mfma_f32_16x16x32_bf16 v[18:21], v[186:189], v[210:213], v[18:21]
	v_mfma_f32_16x16x32_bf16 v[6:9], v[178:181], v[218:221], v[6:9]
	v_mfma_f32_16x16x32_bf16 v[2:5], v[186:189], v[218:221], v[2:5]
	s_setprio 0
	s_barrier
	s_add_i32 s83, s83, 2
	s_add_u32 s81, s81, 0x100
	s_addc_u32 s82, s82, 0
	s_cmpk_gt_u32 s83, 0x53
	s_mov_b64 s[12:13], s[16:17]
	s_cbranch_scc0 .LBB0_948
	v_lshl_add_u32 v142, s63, 8, v146
	v_lshl_or_b32 v140, s22, 8, v148
	v_lshlrev_b32_e32 v141, 12, v142
	v_lshl_add_u32 v150, v140, 1, v141
	v_add_u32_e32 v151, 0x10000, v150
	v_add_u32_e32 v152, 0x20000, v150
	v_add_u32_e32 v153, 0x30000, v150
	v_add_u32_e32 v154, 0x80000, v150
	v_add_u32_e32 v155, 0x90000, v150
	v_add_u32_e32 v156, 0xa0000, v150
	v_add_u32_e32 v157, 0xb0000, v150
	global_load_dwordx4 v[174:177], v150, s[20:21]
	global_load_dwordx4 v[178:181], v150, s[20:21] offset:64
	global_load_dwordx4 v[182:185], v151, s[20:21]
	global_load_dwordx4 v[186:189], v151, s[20:21] offset:64
	global_load_dwordx4 v[190:193], v152, s[20:21]
	global_load_dwordx4 v[194:197], v152, s[20:21] offset:64
	global_load_dwordx4 v[198:201], v153, s[20:21]
	global_load_dwordx4 v[202:205], v153, s[20:21] offset:64
	global_load_dwordx4 v[206:209], v154, s[20:21]
	global_load_dwordx4 v[210:213], v154, s[20:21] offset:64
	global_load_dwordx4 v[214:217], v155, s[20:21]
	global_load_dwordx4 v[218:221], v155, s[20:21] offset:64
	global_load_dwordx4 v[222:225], v156, s[20:21]
	global_load_dwordx4 v[226:229], v156, s[20:21] offset:64
	global_load_dwordx4 v[230:233], v157, s[20:21]
	global_load_dwordx4 v[234:237], v157, s[20:21] offset:64
	s_lshl_b32 s44, s22, 4
	s_lshl_b32 s45, s57, 2
	s_add_i32 s44, s44, s45
	v_lshl_add_u32 v158, v142, 7, s44
	v_add_u32_e32 v159, 0x1000, v158
	v_add_u32_e32 v160, 0x4000, v158
	v_add_u32_e32 v161, 0x5000, v158
	v_xor_b32_e32 v239, 16, v241
	v_xor_b32_e32 v252, 32, v241
	v_lshlrev_b32_e32 v239, 2, v239
	v_lshlrev_b32_e32 v252, 2, v252
	s_and_b64 vcc, exec, s[40:41]
	s_cbranch_vccz .LBB0_951
	s_barrier
